# GEMM K-loops: LDS-DMA addresses in saddr form (no VALU address math in the loader segment) for in-proj, out-proj, GLU, fourier-map, FFT2 loops
# speedup vs baseline: 1.0115x; 1.0115x over previous
.LBB0_367:
	s_add_u32 s6, s4, 0xfff00080
	s_addc_u32 s7, s5, -1
	s_add_i32 s53, 0, 0x10000
	s_cmp_eq_u32 s79, 60
	s_cselect_b32 s31, s27, s7
	s_cselect_b32 s30, s26, s6
	s_cselect_b32 s7, s29, s78
	s_cselect_b32 s6, s28, s55
	s_add_i32 s90, 0, 0x14000
	v_add_u32_e32 v154, s53, v144
	v_add_u32_e32 v170, s90, v144
	ds_read_b128 v[140:143], v154
	ds_read_b128 v[146:149], v154 offset:1024
	ds_read_b128 v[150:153], v154 offset:2048
	ds_read_b128 v[154:157], v154 offset:3072
	ds_read_b128 v[158:161], v170
	ds_read_b128 v[162:165], v170 offset:1024
	ds_read_b128 v[166:169], v170 offset:2048
	ds_read_b128 v[170:173], v170 offset:3072
	s_add_i32 m0, s49, 0xc000
	ds_read_b128 v[188:191], v145
	ds_read_b128 v[192:195], v145 offset:1024
	ds_read_b128 v[196:199], v145 offset:2048
	ds_read_b128 v[200:203], v145 offset:3072
	ds_read_b128 v[204:207], v145 offset:4096
	ds_read_b128 v[208:211], v145 offset:5120
	ds_read_b128 v[212:215], v145 offset:6144
	ds_read_b128 v[216:219], v145 offset:7168
	global_load_lds_dwordx4 v136, s[4:5]
	s_add_i32 m0, s49, 0xe000
	s_nop 0
	global_load_lds_dwordx4 v138, s[4:5]
	s_waitcnt vmcnt(8)
	s_waitcnt lgkmcnt(0)
	s_barrier
	s_setprio 1
	s_waitcnt lgkmcnt(0)
	v_mfma_f32_16x16x32_bf16 v[124:127], v[140:143], v[188:191], v[124:127]
	v_mfma_f32_16x16x32_bf16 v[120:123], v[150:153], v[188:191], v[120:123]
	v_mfma_f32_16x16x32_bf16 v[108:111], v[140:143], v[196:199], v[108:111]
	v_mfma_f32_16x16x32_bf16 v[104:107], v[150:153], v[196:199], v[104:107]
	v_mfma_f32_16x16x32_bf16 v[92:95], v[140:143], v[204:207], v[92:95]
	v_mfma_f32_16x16x32_bf16 v[88:91], v[150:153], v[204:207], v[88:91]
	v_mfma_f32_16x16x32_bf16 v[76:79], v[140:143], v[212:215], v[76:79]
	v_mfma_f32_16x16x32_bf16 v[72:75], v[150:153], v[212:215], v[72:75]
	v_mfma_f32_16x16x32_bf16 v[124:127], v[146:149], v[192:195], v[124:127]
	v_mfma_f32_16x16x32_bf16 v[120:123], v[154:157], v[192:195], v[120:123]
	v_mfma_f32_16x16x32_bf16 v[108:111], v[146:149], v[200:203], v[108:111]
	v_mfma_f32_16x16x32_bf16 v[104:107], v[154:157], v[200:203], v[104:107]
	v_mfma_f32_16x16x32_bf16 v[92:95], v[146:149], v[208:211], v[92:95]
	v_mfma_f32_16x16x32_bf16 v[88:91], v[154:157], v[208:211], v[88:91]
	v_mfma_f32_16x16x32_bf16 v[76:79], v[146:149], v[216:219], v[76:79]
	v_mfma_f32_16x16x32_bf16 v[72:75], v[154:157], v[216:219], v[72:75]
	s_setprio 0
	s_setprio 1
	v_mfma_f32_16x16x32_bf16 v[116:119], v[158:161], v[188:191], v[116:119]
	v_mfma_f32_16x16x32_bf16 v[112:115], v[166:169], v[188:191], v[112:115]
	v_mfma_f32_16x16x32_bf16 v[100:103], v[158:161], v[196:199], v[100:103]
	v_mfma_f32_16x16x32_bf16 v[96:99], v[166:169], v[196:199], v[96:99]
	v_mfma_f32_16x16x32_bf16 v[84:87], v[158:161], v[204:207], v[84:87]
	v_mfma_f32_16x16x32_bf16 v[80:83], v[166:169], v[204:207], v[80:83]
	v_mfma_f32_16x16x32_bf16 v[68:71], v[158:161], v[212:215], v[68:71]
	v_mfma_f32_16x16x32_bf16 v[64:67], v[166:169], v[212:215], v[64:67]
	v_mfma_f32_16x16x32_bf16 v[116:119], v[162:165], v[192:195], v[116:119]
	v_mfma_f32_16x16x32_bf16 v[112:115], v[170:173], v[192:195], v[112:115]
	v_mfma_f32_16x16x32_bf16 v[100:103], v[162:165], v[200:203], v[100:103]
	v_mfma_f32_16x16x32_bf16 v[96:99], v[170:173], v[200:203], v[96:99]
	v_mfma_f32_16x16x32_bf16 v[84:87], v[162:165], v[208:211], v[84:87]
	v_mfma_f32_16x16x32_bf16 v[80:83], v[170:173], v[208:211], v[80:83]
	v_mfma_f32_16x16x32_bf16 v[68:71], v[162:165], v[216:219], v[68:71]
	v_mfma_f32_16x16x32_bf16 v[64:67], v[170:173], v[216:219], v[64:67]
	s_setprio 0
	s_barrier
	s_add_i32 s53, s53, s43
	s_add_u32 s38, s6, 0x80
	s_addc_u32 s39, s7, 0
	s_mov_b32 m0, s53
	ds_read_b128 v[188:191], v145 offset:16384
	ds_read_b128 v[192:195], v145 offset:17408
	ds_read_b128 v[196:199], v145 offset:18432
	ds_read_b128 v[200:203], v145 offset:19456
	ds_read_b128 v[204:207], v145 offset:20480
	ds_read_b128 v[208:211], v145 offset:21504
	ds_read_b128 v[212:215], v145 offset:22528
	ds_read_b128 v[216:219], v145 offset:23552
	global_load_lds_dwordx4 v130, s[6:7]
	s_add_i32 m0, s53, 0x2000
	s_add_u32 s80, s6, 0x100000
	s_addc_u32 s81, s7, 0
	s_add_i32 s53, s90, s43
	global_load_lds_dwordx4 v134, s[6:7]
	s_mov_b32 m0, s53
	s_nop 0
	global_load_lds_dwordx4 v130, s[80:81]
	s_add_i32 m0, s53, 0x2000
	s_nop 0
	global_load_lds_dwordx4 v134, s[80:81]
	s_add_u32 s96, s30, 0x80
	s_addc_u32 s97, s31, 0
	s_mov_b32 m0, s49
	s_nop 0
	global_load_lds_dwordx4 v128, s[30:31]
	s_mov_b32 m0, s15
	s_nop 0
	global_load_lds_dwordx4 v132, s[30:31]
	s_waitcnt vmcnt(8)
	s_waitcnt lgkmcnt(0)
	s_barrier
	s_setprio 1
	s_waitcnt lgkmcnt(0)
	v_mfma_f32_16x16x32_bf16 v[60:63], v[140:143], v[188:191], v[60:63]
	v_mfma_f32_16x16x32_bf16 v[56:59], v[150:153], v[188:191], v[56:59]
	v_mfma_f32_16x16x32_bf16 v[44:47], v[140:143], v[196:199], v[44:47]
	v_mfma_f32_16x16x32_bf16 v[40:43], v[150:153], v[196:199], v[40:43]
	v_mfma_f32_16x16x32_bf16 v[28:31], v[140:143], v[204:207], v[28:31]
	v_mfma_f32_16x16x32_bf16 v[24:27], v[150:153], v[204:207], v[24:27]
	v_mfma_f32_16x16x32_bf16 v[12:15], v[140:143], v[212:215], v[12:15]
	v_mfma_f32_16x16x32_bf16 v[8:11], v[150:153], v[212:215], v[8:11]
	v_mfma_f32_16x16x32_bf16 v[60:63], v[146:149], v[192:195], v[60:63]
	v_mfma_f32_16x16x32_bf16 v[56:59], v[154:157], v[192:195], v[56:59]
	v_mfma_f32_16x16x32_bf16 v[44:47], v[146:149], v[200:203], v[44:47]
	v_mfma_f32_16x16x32_bf16 v[40:43], v[154:157], v[200:203], v[40:43]
	v_mfma_f32_16x16x32_bf16 v[28:31], v[146:149], v[208:211], v[28:31]
	v_mfma_f32_16x16x32_bf16 v[24:27], v[154:157], v[208:211], v[24:27]
	v_mfma_f32_16x16x32_bf16 v[12:15], v[146:149], v[216:219], v[12:15]
	v_mfma_f32_16x16x32_bf16 v[8:11], v[154:157], v[216:219], v[8:11]
	s_setprio 0
	s_setprio 1
	v_mfma_f32_16x16x32_bf16 v[52:55], v[158:161], v[188:191], v[52:55]
	v_mfma_f32_16x16x32_bf16 v[48:51], v[166:169], v[188:191], v[48:51]
	v_mfma_f32_16x16x32_bf16 v[36:39], v[158:161], v[196:199], v[36:39]
	v_mfma_f32_16x16x32_bf16 v[32:35], v[166:169], v[196:199], v[32:35]
	v_mfma_f32_16x16x32_bf16 v[20:23], v[158:161], v[204:207], v[20:23]
	v_mfma_f32_16x16x32_bf16 v[16:19], v[166:169], v[204:207], v[16:19]
	v_mfma_f32_16x16x32_bf16 v[4:7], v[158:161], v[212:215], v[4:7]
	v_mfma_f32_16x16x32_bf16 v[0:3], v[166:169], v[212:215], v[0:3]
	v_mfma_f32_16x16x32_bf16 v[52:55], v[162:165], v[192:195], v[52:55]
	v_mfma_f32_16x16x32_bf16 v[48:51], v[170:173], v[192:195], v[48:51]
	v_mfma_f32_16x16x32_bf16 v[36:39], v[162:165], v[200:203], v[36:39]
	v_mfma_f32_16x16x32_bf16 v[32:35], v[170:173], v[200:203], v[32:35]
	v_mfma_f32_16x16x32_bf16 v[20:23], v[162:165], v[208:211], v[20:23]
	v_mfma_f32_16x16x32_bf16 v[16:19], v[170:173], v[208:211], v[16:19]
	v_mfma_f32_16x16x32_bf16 v[4:7], v[162:165], v[216:219], v[4:7]
	v_mfma_f32_16x16x32_bf16 v[0:3], v[170:173], v[216:219], v[0:3]
	s_setprio 0
	s_barrier
	s_add_i32 s53, 0, 0x18000
	s_add_i32 s80, 0, 0x1c000
	v_add_u32_e32 v154, s53, v144
	v_add_u32_e32 v170, s80, v144
	ds_read_b128 v[140:143], v154
	ds_read_b128 v[146:149], v154 offset:1024
	ds_read_b128 v[150:153], v154 offset:2048
	ds_read_b128 v[154:157], v154 offset:3072
	ds_read_b128 v[158:161], v170
	ds_read_b128 v[162:165], v170 offset:1024
	ds_read_b128 v[166:169], v170 offset:2048
	ds_read_b128 v[170:173], v170 offset:3072
	s_add_u32 s30, s30, 0x100000
	s_addc_u32 s31, s31, 0
	s_mov_b32 m0, s36
	ds_read_b128 v[188:191], v145 offset:32768
	ds_read_b128 v[192:195], v145 offset:33792
	ds_read_b128 v[196:199], v145 offset:34816
	ds_read_b128 v[200:203], v145 offset:35840
	ds_read_b128 v[204:207], v145 offset:36864
	ds_read_b128 v[208:211], v145 offset:37888
	ds_read_b128 v[212:215], v145 offset:38912
	ds_read_b128 v[216:219], v145 offset:39936
	global_load_lds_dwordx4 v128, s[30:31]
	s_mov_b32 m0, s50
	s_nop 0
	global_load_lds_dwordx4 v132, s[30:31]
	s_waitcnt vmcnt(8)
	s_waitcnt lgkmcnt(0)
	s_barrier
	s_setprio 1
	s_waitcnt lgkmcnt(0)
	v_mfma_f32_16x16x32_bf16 v[124:127], v[140:143], v[188:191], v[124:127]
	v_mfma_f32_16x16x32_bf16 v[120:123], v[150:153], v[188:191], v[120:123]
	v_mfma_f32_16x16x32_bf16 v[108:111], v[140:143], v[196:199], v[108:111]
	v_mfma_f32_16x16x32_bf16 v[104:107], v[150:153], v[196:199], v[104:107]
	v_mfma_f32_16x16x32_bf16 v[92:95], v[140:143], v[204:207], v[92:95]
	v_mfma_f32_16x16x32_bf16 v[88:91], v[150:153], v[204:207], v[88:91]
	v_mfma_f32_16x16x32_bf16 v[76:79], v[140:143], v[212:215], v[76:79]
	v_mfma_f32_16x16x32_bf16 v[72:75], v[150:153], v[212:215], v[72:75]
	v_mfma_f32_16x16x32_bf16 v[124:127], v[146:149], v[192:195], v[124:127]
	v_mfma_f32_16x16x32_bf16 v[120:123], v[154:157], v[192:195], v[120:123]
	v_mfma_f32_16x16x32_bf16 v[108:111], v[146:149], v[200:203], v[108:111]
	v_mfma_f32_16x16x32_bf16 v[104:107], v[154:157], v[200:203], v[104:107]
	v_mfma_f32_16x16x32_bf16 v[92:95], v[146:149], v[208:211], v[92:95]
	v_mfma_f32_16x16x32_bf16 v[88:91], v[154:157], v[208:211], v[88:91]
	v_mfma_f32_16x16x32_bf16 v[76:79], v[146:149], v[216:219], v[76:79]
	v_mfma_f32_16x16x32_bf16 v[72:75], v[154:157], v[216:219], v[72:75]
	s_setprio 0
	s_setprio 1
	v_mfma_f32_16x16x32_bf16 v[116:119], v[158:161], v[188:191], v[116:119]
	v_mfma_f32_16x16x32_bf16 v[112:115], v[166:169], v[188:191], v[112:115]
	v_mfma_f32_16x16x32_bf16 v[100:103], v[158:161], v[196:199], v[100:103]
	v_mfma_f32_16x16x32_bf16 v[96:99], v[166:169], v[196:199], v[96:99]
	v_mfma_f32_16x16x32_bf16 v[84:87], v[158:161], v[204:207], v[84:87]
	v_mfma_f32_16x16x32_bf16 v[80:83], v[166:169], v[204:207], v[80:83]
	v_mfma_f32_16x16x32_bf16 v[68:71], v[158:161], v[212:215], v[68:71]
	v_mfma_f32_16x16x32_bf16 v[64:67], v[166:169], v[212:215], v[64:67]
	v_mfma_f32_16x16x32_bf16 v[116:119], v[162:165], v[192:195], v[116:119]
	v_mfma_f32_16x16x32_bf16 v[112:115], v[170:173], v[192:195], v[112:115]
	v_mfma_f32_16x16x32_bf16 v[100:103], v[162:165], v[200:203], v[100:103]
	v_mfma_f32_16x16x32_bf16 v[96:99], v[170:173], v[200:203], v[96:99]
	v_mfma_f32_16x16x32_bf16 v[84:87], v[162:165], v[208:211], v[84:87]
	v_mfma_f32_16x16x32_bf16 v[80:83], v[170:173], v[208:211], v[80:83]
	v_mfma_f32_16x16x32_bf16 v[68:71], v[162:165], v[216:219], v[68:71]
	v_mfma_f32_16x16x32_bf16 v[64:67], v[170:173], v[216:219], v[64:67]
	s_setprio 0
	s_barrier
	s_add_i32 s30, s53, s43
	s_mov_b32 m0, s30
	ds_read_b128 v[188:191], v145 offset:49152
	ds_read_b128 v[192:195], v145 offset:50176
	ds_read_b128 v[196:199], v145 offset:51200
	ds_read_b128 v[200:203], v145 offset:52224
	ds_read_b128 v[204:207], v145 offset:53248
	ds_read_b128 v[208:211], v145 offset:54272
	ds_read_b128 v[212:215], v145 offset:55296
	ds_read_b128 v[216:219], v145 offset:56320
	global_load_lds_dwordx4 v130, s[38:39]
	s_add_i32 m0, s30, 0x2000
	s_add_u32 s6, s6, 0x100080
	s_addc_u32 s7, s7, 0
	s_add_i32 s30, s80, s43
	global_load_lds_dwordx4 v134, s[38:39]
	s_mov_b32 m0, s30
	s_nop 0
	global_load_lds_dwordx4 v130, s[6:7]
	s_add_i32 m0, s30, 0x2000
	s_nop 0
	global_load_lds_dwordx4 v134, s[6:7]
	s_mov_b32 m0, s51
	s_nop 0
	global_load_lds_dwordx4 v128, s[96:97]
	s_mov_b32 m0, s52
	s_nop 0
	global_load_lds_dwordx4 v132, s[96:97]
	s_waitcnt vmcnt(8)
	s_waitcnt lgkmcnt(0)
	s_barrier
	s_setprio 1
	s_waitcnt lgkmcnt(0)
	v_mfma_f32_16x16x32_bf16 v[60:63], v[140:143], v[188:191], v[60:63]
	v_mfma_f32_16x16x32_bf16 v[56:59], v[150:153], v[188:191], v[56:59]
	v_mfma_f32_16x16x32_bf16 v[44:47], v[140:143], v[196:199], v[44:47]
	v_mfma_f32_16x16x32_bf16 v[40:43], v[150:153], v[196:199], v[40:43]
	v_mfma_f32_16x16x32_bf16 v[28:31], v[140:143], v[204:207], v[28:31]
	v_mfma_f32_16x16x32_bf16 v[24:27], v[150:153], v[204:207], v[24:27]
	v_mfma_f32_16x16x32_bf16 v[12:15], v[140:143], v[212:215], v[12:15]
	v_mfma_f32_16x16x32_bf16 v[8:11], v[150:153], v[212:215], v[8:11]
	v_mfma_f32_16x16x32_bf16 v[60:63], v[146:149], v[192:195], v[60:63]
	v_mfma_f32_16x16x32_bf16 v[56:59], v[154:157], v[192:195], v[56:59]
	v_mfma_f32_16x16x32_bf16 v[44:47], v[146:149], v[200:203], v[44:47]
	v_mfma_f32_16x16x32_bf16 v[40:43], v[154:157], v[200:203], v[40:43]
	v_mfma_f32_16x16x32_bf16 v[28:31], v[146:149], v[208:211], v[28:31]
	v_mfma_f32_16x16x32_bf16 v[24:27], v[154:157], v[208:211], v[24:27]
	v_mfma_f32_16x16x32_bf16 v[12:15], v[146:149], v[216:219], v[12:15]
	v_mfma_f32_16x16x32_bf16 v[8:11], v[154:157], v[216:219], v[8:11]
	s_setprio 0
	s_setprio 1
	v_mfma_f32_16x16x32_bf16 v[52:55], v[158:161], v[188:191], v[52:55]
	v_mfma_f32_16x16x32_bf16 v[48:51], v[166:169], v[188:191], v[48:51]
	v_mfma_f32_16x16x32_bf16 v[36:39], v[158:161], v[196:199], v[36:39]
	v_mfma_f32_16x16x32_bf16 v[32:35], v[166:169], v[196:199], v[32:35]
	v_mfma_f32_16x16x32_bf16 v[20:23], v[158:161], v[204:207], v[20:23]
	v_mfma_f32_16x16x32_bf16 v[16:19], v[166:169], v[204:207], v[16:19]
	v_mfma_f32_16x16x32_bf16 v[4:7], v[158:161], v[212:215], v[4:7]
	v_mfma_f32_16x16x32_bf16 v[0:3], v[166:169], v[212:215], v[0:3]
	v_mfma_f32_16x16x32_bf16 v[52:55], v[162:165], v[192:195], v[52:55]
	v_mfma_f32_16x16x32_bf16 v[48:51], v[170:173], v[192:195], v[48:51]
	v_mfma_f32_16x16x32_bf16 v[36:39], v[162:165], v[200:203], v[36:39]
	v_mfma_f32_16x16x32_bf16 v[32:35], v[170:173], v[200:203], v[32:35]
	v_mfma_f32_16x16x32_bf16 v[20:23], v[162:165], v[208:211], v[20:23]
	v_mfma_f32_16x16x32_bf16 v[16:19], v[170:173], v[208:211], v[16:19]
	v_mfma_f32_16x16x32_bf16 v[4:7], v[162:165], v[216:219], v[4:7]
	v_mfma_f32_16x16x32_bf16 v[0:3], v[170:173], v[216:219], v[0:3]
	s_setprio 0
	s_barrier
	s_add_i32 s79, s79, 2
	s_add_u32 s4, s4, 0x100
	s_addc_u32 s5, s5, 0
	s_add_u32 s55, s55, 0x100
	s_addc_u32 s78, s78, 0
	s_cmp_gt_u32 s79, 61
	s_cbranch_scc0 .LBB0_367
	s_and_b64 vcc, exec, s[24:25]
	s_cbranch_vccz .LBB0_370
	s_barrier

.LBB0_687:
	s_add_u32 s26, s24, 0xffe00080
	s_addc_u32 s27, s25, -1
	s_add_i32 s53, 0, 0x10000
	s_cmp_eq_u32 s79, 60
	s_cselect_b32 s29, s7, s27
	s_cselect_b32 s28, s6, s26
	s_cselect_b32 s27, s19, s78
	s_cselect_b32 s26, s18, s57
	s_add_i32 s85, 0, 0x14000
	v_add_u32_e32 v152, s53, v142
	v_add_u32_e32 v168, s85, v142
	ds_read_b128 v[138:141], v152
	ds_read_b128 v[144:147], v152 offset:1024
	ds_read_b128 v[148:151], v152 offset:2048
	ds_read_b128 v[152:155], v152 offset:3072
	ds_read_b128 v[156:159], v168
	ds_read_b128 v[160:163], v168 offset:1024
	ds_read_b128 v[164:167], v168 offset:2048
	ds_read_b128 v[168:171], v168 offset:3072
	s_add_i32 m0, s31, 0xc000
	ds_read_b128 v[172:175], v143
	ds_read_b128 v[188:191], v143 offset:1024
	ds_read_b128 v[192:195], v143 offset:2048
	ds_read_b128 v[196:199], v143 offset:3072
	ds_read_b128 v[200:203], v143 offset:4096
	ds_read_b128 v[204:207], v143 offset:5120
	ds_read_b128 v[208:211], v143 offset:6144
	ds_read_b128 v[212:215], v143 offset:7168
	global_load_lds_dwordx4 v134, s[24:25]
	s_add_i32 m0, s31, 0xe000
	s_nop 0
	global_load_lds_dwordx4 v136, s[24:25]
	s_waitcnt vmcnt(8)
	s_waitcnt lgkmcnt(0)
	s_barrier
	s_setprio 1
	s_waitcnt lgkmcnt(0)
	v_mfma_f32_16x16x32_bf16 v[124:127], v[138:141], v[172:175], v[124:127]
	v_mfma_f32_16x16x32_bf16 v[120:123], v[148:151], v[172:175], v[120:123]
	v_mfma_f32_16x16x32_bf16 v[108:111], v[138:141], v[192:195], v[108:111]
	v_mfma_f32_16x16x32_bf16 v[104:107], v[148:151], v[192:195], v[104:107]
	v_mfma_f32_16x16x32_bf16 v[92:95], v[138:141], v[200:203], v[92:95]
	v_mfma_f32_16x16x32_bf16 v[88:91], v[148:151], v[200:203], v[88:91]
	v_mfma_f32_16x16x32_bf16 v[76:79], v[138:141], v[208:211], v[76:79]
	v_mfma_f32_16x16x32_bf16 v[72:75], v[148:151], v[208:211], v[72:75]
	v_mfma_f32_16x16x32_bf16 v[124:127], v[144:147], v[188:191], v[124:127]
	v_mfma_f32_16x16x32_bf16 v[120:123], v[152:155], v[188:191], v[120:123]
	v_mfma_f32_16x16x32_bf16 v[108:111], v[144:147], v[196:199], v[108:111]
	v_mfma_f32_16x16x32_bf16 v[104:107], v[152:155], v[196:199], v[104:107]
	v_mfma_f32_16x16x32_bf16 v[92:95], v[144:147], v[204:207], v[92:95]
	v_mfma_f32_16x16x32_bf16 v[88:91], v[152:155], v[204:207], v[88:91]
	v_mfma_f32_16x16x32_bf16 v[76:79], v[144:147], v[212:215], v[76:79]
	v_mfma_f32_16x16x32_bf16 v[72:75], v[152:155], v[212:215], v[72:75]
	s_setprio 0
	s_setprio 1
	v_mfma_f32_16x16x32_bf16 v[116:119], v[156:159], v[172:175], v[116:119]
	v_mfma_f32_16x16x32_bf16 v[112:115], v[164:167], v[172:175], v[112:115]
	v_mfma_f32_16x16x32_bf16 v[100:103], v[156:159], v[192:195], v[100:103]
	v_mfma_f32_16x16x32_bf16 v[96:99], v[164:167], v[192:195], v[96:99]
	v_mfma_f32_16x16x32_bf16 v[84:87], v[156:159], v[200:203], v[84:87]
	v_mfma_f32_16x16x32_bf16 v[80:83], v[164:167], v[200:203], v[80:83]
	v_mfma_f32_16x16x32_bf16 v[68:71], v[156:159], v[208:211], v[68:71]
	v_mfma_f32_16x16x32_bf16 v[64:67], v[164:167], v[208:211], v[64:67]
	v_mfma_f32_16x16x32_bf16 v[116:119], v[160:163], v[188:191], v[116:119]
	v_mfma_f32_16x16x32_bf16 v[112:115], v[168:171], v[188:191], v[112:115]
	v_mfma_f32_16x16x32_bf16 v[100:103], v[160:163], v[196:199], v[100:103]
	v_mfma_f32_16x16x32_bf16 v[96:99], v[168:171], v[196:199], v[96:99]
	v_mfma_f32_16x16x32_bf16 v[84:87], v[160:163], v[204:207], v[84:87]
	v_mfma_f32_16x16x32_bf16 v[80:83], v[168:171], v[204:207], v[80:83]
	v_mfma_f32_16x16x32_bf16 v[68:71], v[160:163], v[212:215], v[68:71]
	v_mfma_f32_16x16x32_bf16 v[64:67], v[168:171], v[212:215], v[64:67]
	s_setprio 0
	s_barrier
	s_add_i32 s53, s53, s30
	s_add_u32 s90, s26, 0x80
	s_addc_u32 s91, s27, 0
	s_mov_b32 m0, s53
	ds_read_b128 v[172:175], v143 offset:16384
	ds_read_b128 v[188:191], v143 offset:17408
	ds_read_b128 v[192:195], v143 offset:18432
	ds_read_b128 v[196:199], v143 offset:19456
	ds_read_b128 v[200:203], v143 offset:20480
	ds_read_b128 v[204:207], v143 offset:21504
	ds_read_b128 v[208:211], v143 offset:22528
	ds_read_b128 v[212:215], v143 offset:23552
	global_load_lds_dwordx4 v176, s[26:27]
	s_add_i32 m0, s53, 0x2000
	s_add_u32 s80, s26, 0x100000
	s_addc_u32 s81, s27, 0
	s_add_i32 s53, s85, s30
	global_load_lds_dwordx4 v128, s[26:27]
	s_mov_b32 m0, s53
	s_nop 0
	global_load_lds_dwordx4 v176, s[80:81]
	s_add_i32 m0, s53, 0x2000
	s_nop 0
	global_load_lds_dwordx4 v128, s[80:81]
	s_add_u32 s98, s28, 0x80
	s_addc_u32 s99, s29, 0
	s_mov_b32 m0, s31
	s_nop 0
	global_load_lds_dwordx4 v132, s[28:29]
	s_mov_b32 m0, s34
	s_nop 0
	global_load_lds_dwordx4 v130, s[28:29]
	s_waitcnt vmcnt(8)
	s_waitcnt lgkmcnt(0)
	s_barrier
	s_setprio 1
	s_waitcnt lgkmcnt(0)
	v_mfma_f32_16x16x32_bf16 v[60:63], v[138:141], v[172:175], v[60:63]
	v_mfma_f32_16x16x32_bf16 v[56:59], v[148:151], v[172:175], v[56:59]
	v_mfma_f32_16x16x32_bf16 v[44:47], v[138:141], v[192:195], v[44:47]
	v_mfma_f32_16x16x32_bf16 v[40:43], v[148:151], v[192:195], v[40:43]
	v_mfma_f32_16x16x32_bf16 v[28:31], v[138:141], v[200:203], v[28:31]
	v_mfma_f32_16x16x32_bf16 v[24:27], v[148:151], v[200:203], v[24:27]
	v_mfma_f32_16x16x32_bf16 v[12:15], v[138:141], v[208:211], v[12:15]
	v_mfma_f32_16x16x32_bf16 v[8:11], v[148:151], v[208:211], v[8:11]
	v_mfma_f32_16x16x32_bf16 v[60:63], v[144:147], v[188:191], v[60:63]
	v_mfma_f32_16x16x32_bf16 v[56:59], v[152:155], v[188:191], v[56:59]
	v_mfma_f32_16x16x32_bf16 v[44:47], v[144:147], v[196:199], v[44:47]
	v_mfma_f32_16x16x32_bf16 v[40:43], v[152:155], v[196:199], v[40:43]
	v_mfma_f32_16x16x32_bf16 v[28:31], v[144:147], v[204:207], v[28:31]
	v_mfma_f32_16x16x32_bf16 v[24:27], v[152:155], v[204:207], v[24:27]
	v_mfma_f32_16x16x32_bf16 v[12:15], v[144:147], v[212:215], v[12:15]
	v_mfma_f32_16x16x32_bf16 v[8:11], v[152:155], v[212:215], v[8:11]
	s_setprio 0
	s_setprio 1
	v_mfma_f32_16x16x32_bf16 v[52:55], v[156:159], v[172:175], v[52:55]
	v_mfma_f32_16x16x32_bf16 v[48:51], v[164:167], v[172:175], v[48:51]
	v_mfma_f32_16x16x32_bf16 v[36:39], v[156:159], v[192:195], v[36:39]
	v_mfma_f32_16x16x32_bf16 v[32:35], v[164:167], v[192:195], v[32:35]
	v_mfma_f32_16x16x32_bf16 v[20:23], v[156:159], v[200:203], v[20:23]
	v_mfma_f32_16x16x32_bf16 v[16:19], v[164:167], v[200:203], v[16:19]
	v_mfma_f32_16x16x32_bf16 v[4:7], v[156:159], v[208:211], v[4:7]
	v_mfma_f32_16x16x32_bf16 v[0:3], v[164:167], v[208:211], v[0:3]
	v_mfma_f32_16x16x32_bf16 v[52:55], v[160:163], v[188:191], v[52:55]
	v_mfma_f32_16x16x32_bf16 v[48:51], v[168:171], v[188:191], v[48:51]
	v_mfma_f32_16x16x32_bf16 v[36:39], v[160:163], v[196:199], v[36:39]
	v_mfma_f32_16x16x32_bf16 v[32:35], v[168:171], v[196:199], v[32:35]
	v_mfma_f32_16x16x32_bf16 v[20:23], v[160:163], v[204:207], v[20:23]
	v_mfma_f32_16x16x32_bf16 v[16:19], v[168:171], v[204:207], v[16:19]
	v_mfma_f32_16x16x32_bf16 v[4:7], v[160:163], v[212:215], v[4:7]
	v_mfma_f32_16x16x32_bf16 v[0:3], v[168:171], v[212:215], v[0:3]
	s_setprio 0
	s_barrier
	s_add_i32 s53, 0, 0x18000
	s_add_i32 s80, 0, 0x1c000
	v_add_u32_e32 v152, s53, v142
	v_add_u32_e32 v168, s80, v142
	ds_read_b128 v[138:141], v152
	ds_read_b128 v[144:147], v152 offset:1024
	ds_read_b128 v[148:151], v152 offset:2048
	ds_read_b128 v[152:155], v152 offset:3072
	ds_read_b128 v[156:159], v168
	ds_read_b128 v[160:163], v168 offset:1024
	ds_read_b128 v[164:167], v168 offset:2048
	ds_read_b128 v[168:171], v168 offset:3072
	s_add_u32 s28, s28, 0x200000
	s_addc_u32 s29, s29, 0
	s_mov_b32 m0, s35
	ds_read_b128 v[172:175], v143 offset:32768
	ds_read_b128 v[188:191], v143 offset:33792
	ds_read_b128 v[192:195], v143 offset:34816
	ds_read_b128 v[196:199], v143 offset:35840
	ds_read_b128 v[200:203], v143 offset:36864
	ds_read_b128 v[204:207], v143 offset:37888
	ds_read_b128 v[208:211], v143 offset:38912
	ds_read_b128 v[212:215], v143 offset:39936
	global_load_lds_dwordx4 v132, s[28:29]
	s_mov_b32 m0, s36
	s_nop 0
	global_load_lds_dwordx4 v130, s[28:29]
	s_waitcnt vmcnt(8)
	s_waitcnt lgkmcnt(0)
	s_barrier
	s_setprio 1
	s_waitcnt lgkmcnt(0)
	v_mfma_f32_16x16x32_bf16 v[124:127], v[138:141], v[172:175], v[124:127]
	v_mfma_f32_16x16x32_bf16 v[120:123], v[148:151], v[172:175], v[120:123]
	v_mfma_f32_16x16x32_bf16 v[108:111], v[138:141], v[192:195], v[108:111]
	v_mfma_f32_16x16x32_bf16 v[104:107], v[148:151], v[192:195], v[104:107]
	v_mfma_f32_16x16x32_bf16 v[92:95], v[138:141], v[200:203], v[92:95]
	v_mfma_f32_16x16x32_bf16 v[88:91], v[148:151], v[200:203], v[88:91]
	v_mfma_f32_16x16x32_bf16 v[76:79], v[138:141], v[208:211], v[76:79]
	v_mfma_f32_16x16x32_bf16 v[72:75], v[148:151], v[208:211], v[72:75]
	v_mfma_f32_16x16x32_bf16 v[124:127], v[144:147], v[188:191], v[124:127]
	v_mfma_f32_16x16x32_bf16 v[120:123], v[152:155], v[188:191], v[120:123]
	v_mfma_f32_16x16x32_bf16 v[108:111], v[144:147], v[196:199], v[108:111]
	v_mfma_f32_16x16x32_bf16 v[104:107], v[152:155], v[196:199], v[104:107]
	v_mfma_f32_16x16x32_bf16 v[92:95], v[144:147], v[204:207], v[92:95]
	v_mfma_f32_16x16x32_bf16 v[88:91], v[152:155], v[204:207], v[88:91]
	v_mfma_f32_16x16x32_bf16 v[76:79], v[144:147], v[212:215], v[76:79]
	v_mfma_f32_16x16x32_bf16 v[72:75], v[152:155], v[212:215], v[72:75]
	s_setprio 0
	s_setprio 1
	v_mfma_f32_16x16x32_bf16 v[116:119], v[156:159], v[172:175], v[116:119]
	v_mfma_f32_16x16x32_bf16 v[112:115], v[164:167], v[172:175], v[112:115]
	v_mfma_f32_16x16x32_bf16 v[100:103], v[156:159], v[192:195], v[100:103]
	v_mfma_f32_16x16x32_bf16 v[96:99], v[164:167], v[192:195], v[96:99]
	v_mfma_f32_16x16x32_bf16 v[84:87], v[156:159], v[200:203], v[84:87]
	v_mfma_f32_16x16x32_bf16 v[80:83], v[164:167], v[200:203], v[80:83]
	v_mfma_f32_16x16x32_bf16 v[68:71], v[156:159], v[208:211], v[68:71]
	v_mfma_f32_16x16x32_bf16 v[64:67], v[164:167], v[208:211], v[64:67]
	v_mfma_f32_16x16x32_bf16 v[116:119], v[160:163], v[188:191], v[116:119]
	v_mfma_f32_16x16x32_bf16 v[112:115], v[168:171], v[188:191], v[112:115]
	v_mfma_f32_16x16x32_bf16 v[100:103], v[160:163], v[196:199], v[100:103]
	v_mfma_f32_16x16x32_bf16 v[96:99], v[168:171], v[196:199], v[96:99]
	v_mfma_f32_16x16x32_bf16 v[84:87], v[160:163], v[204:207], v[84:87]
	v_mfma_f32_16x16x32_bf16 v[80:83], v[168:171], v[204:207], v[80:83]
	v_mfma_f32_16x16x32_bf16 v[68:71], v[160:163], v[212:215], v[68:71]
	v_mfma_f32_16x16x32_bf16 v[64:67], v[168:171], v[212:215], v[64:67]
	s_setprio 0
	s_barrier
	s_add_i32 s28, s53, s30
	s_mov_b32 m0, s28
	ds_read_b128 v[172:175], v143 offset:49152
	ds_read_b128 v[188:191], v143 offset:50176
	ds_read_b128 v[192:195], v143 offset:51200
	ds_read_b128 v[196:199], v143 offset:52224
	ds_read_b128 v[200:203], v143 offset:53248
	ds_read_b128 v[204:207], v143 offset:54272
	ds_read_b128 v[208:211], v143 offset:55296
	ds_read_b128 v[212:215], v143 offset:56320
	global_load_lds_dwordx4 v176, s[90:91]
	s_add_i32 m0, s28, 0x2000
	s_add_u32 s26, s26, 0x100080
	s_addc_u32 s27, s27, 0
	s_add_i32 s28, s80, s30
	global_load_lds_dwordx4 v128, s[90:91]
	s_mov_b32 m0, s28
	s_nop 0
	global_load_lds_dwordx4 v176, s[26:27]
	s_add_i32 m0, s28, 0x2000
	s_nop 0
	global_load_lds_dwordx4 v128, s[26:27]
	s_mov_b32 m0, s44
	s_nop 0
	global_load_lds_dwordx4 v132, s[98:99]
	s_mov_b32 m0, s48
	s_nop 0
	global_load_lds_dwordx4 v130, s[98:99]
	s_waitcnt vmcnt(8)
	s_waitcnt lgkmcnt(0)
	s_barrier
	s_setprio 1
	s_waitcnt lgkmcnt(0)
	v_mfma_f32_16x16x32_bf16 v[60:63], v[138:141], v[172:175], v[60:63]
	v_mfma_f32_16x16x32_bf16 v[56:59], v[148:151], v[172:175], v[56:59]
	v_mfma_f32_16x16x32_bf16 v[44:47], v[138:141], v[192:195], v[44:47]
	v_mfma_f32_16x16x32_bf16 v[40:43], v[148:151], v[192:195], v[40:43]
	v_mfma_f32_16x16x32_bf16 v[28:31], v[138:141], v[200:203], v[28:31]
	v_mfma_f32_16x16x32_bf16 v[24:27], v[148:151], v[200:203], v[24:27]
	v_mfma_f32_16x16x32_bf16 v[12:15], v[138:141], v[208:211], v[12:15]
	v_mfma_f32_16x16x32_bf16 v[8:11], v[148:151], v[208:211], v[8:11]
	v_mfma_f32_16x16x32_bf16 v[60:63], v[144:147], v[188:191], v[60:63]
	v_mfma_f32_16x16x32_bf16 v[56:59], v[152:155], v[188:191], v[56:59]
	v_mfma_f32_16x16x32_bf16 v[44:47], v[144:147], v[196:199], v[44:47]
	v_mfma_f32_16x16x32_bf16 v[40:43], v[152:155], v[196:199], v[40:43]
	v_mfma_f32_16x16x32_bf16 v[28:31], v[144:147], v[204:207], v[28:31]
	v_mfma_f32_16x16x32_bf16 v[24:27], v[152:155], v[204:207], v[24:27]
	v_mfma_f32_16x16x32_bf16 v[12:15], v[144:147], v[212:215], v[12:15]
	v_mfma_f32_16x16x32_bf16 v[8:11], v[152:155], v[212:215], v[8:11]
	s_setprio 0
	s_setprio 1
	v_mfma_f32_16x16x32_bf16 v[52:55], v[156:159], v[172:175], v[52:55]
	v_mfma_f32_16x16x32_bf16 v[48:51], v[164:167], v[172:175], v[48:51]
	v_mfma_f32_16x16x32_bf16 v[36:39], v[156:159], v[192:195], v[36:39]
	v_mfma_f32_16x16x32_bf16 v[32:35], v[164:167], v[192:195], v[32:35]
	v_mfma_f32_16x16x32_bf16 v[20:23], v[156:159], v[200:203], v[20:23]
	v_mfma_f32_16x16x32_bf16 v[16:19], v[164:167], v[200:203], v[16:19]
	v_mfma_f32_16x16x32_bf16 v[4:7], v[156:159], v[208:211], v[4:7]
	v_mfma_f32_16x16x32_bf16 v[0:3], v[164:167], v[208:211], v[0:3]
	v_mfma_f32_16x16x32_bf16 v[52:55], v[160:163], v[188:191], v[52:55]
	v_mfma_f32_16x16x32_bf16 v[48:51], v[168:171], v[188:191], v[48:51]
	v_mfma_f32_16x16x32_bf16 v[36:39], v[160:163], v[196:199], v[36:39]
	v_mfma_f32_16x16x32_bf16 v[32:35], v[168:171], v[196:199], v[32:35]
	v_mfma_f32_16x16x32_bf16 v[20:23], v[160:163], v[204:207], v[20:23]
	v_mfma_f32_16x16x32_bf16 v[16:19], v[168:171], v[204:207], v[16:19]
	v_mfma_f32_16x16x32_bf16 v[4:7], v[160:163], v[212:215], v[4:7]
	v_mfma_f32_16x16x32_bf16 v[0:3], v[168:171], v[212:215], v[0:3]
	s_setprio 0
	s_barrier
	s_add_i32 s79, s79, 2
	s_add_u32 s24, s24, 0x100
	s_addc_u32 s25, s25, 0
	s_add_u32 s57, s57, 0x100
	s_addc_u32 s78, s78, 0
	s_cmp_gt_u32 s79, 61
	s_cbranch_scc0 .LBB0_687
	s_and_b64 vcc, exec, s[4:5]
	s_cbranch_vccz .LBB0_690
	s_barrier

.LBB0_761:
	s_add_u32 s34, s30, 0xfffc0080
	s_addc_u32 s35, s31, -1
	s_add_i32 s38, 0, 0x10000
	s_cmp_eq_u32 s79, 12
	s_cselect_b32 s49, s27, s35
	s_cselect_b32 s48, s26, s34
	v_add_u32_e32 v142, s38, v144
	s_cselect_b32 s35, s29, s78
	s_cselect_b32 s34, s28, s55
	s_add_i32 s39, 0, 0x14000
	ds_read_b128 v[138:141], v142
	ds_read_b128 v[146:149], v142 offset:1024
	ds_read_b128 v[150:153], v142 offset:2048
	ds_read_b128 v[154:157], v142 offset:3072
	v_add_u32_e32 v142, s39, v144
	ds_read_b128 v[158:161], v142
	ds_read_b128 v[162:165], v142 offset:1024
	ds_read_b128 v[166:169], v142 offset:2048
	ds_read_b128 v[170:173], v142 offset:3072
	s_add_i32 m0, s10, 0xc000
	ds_read_b128 v[178:181], v145
	ds_read_b128 v[182:185], v145 offset:1024
	ds_read_b128 v[188:191], v145 offset:2048
	ds_read_b128 v[192:195], v145 offset:3072
	ds_read_b128 v[196:199], v145 offset:4096
	ds_read_b128 v[200:203], v145 offset:5120
	ds_read_b128 v[204:207], v145 offset:6144
	ds_read_b128 v[208:211], v145 offset:7168
	global_load_lds_dwordx4 v134, s[30:31]
	s_add_i32 m0, s10, 0xe000
	s_nop 0
	global_load_lds_dwordx4 v136, s[30:31]
	s_waitcnt vmcnt(8)
	s_waitcnt lgkmcnt(0)
	s_barrier
	s_setprio 1
	s_waitcnt lgkmcnt(0)
	v_mfma_f32_16x16x32_bf16 v[124:127], v[138:141], v[178:181], v[124:127]
	v_mfma_f32_16x16x32_bf16 v[112:115], v[150:153], v[178:181], v[112:115]
	v_mfma_f32_16x16x32_bf16 v[108:111], v[138:141], v[188:191], v[108:111]
	v_mfma_f32_16x16x32_bf16 v[96:99], v[150:153], v[188:191], v[96:99]
	v_mfma_f32_16x16x32_bf16 v[92:95], v[138:141], v[196:199], v[92:95]
	v_mfma_f32_16x16x32_bf16 v[80:83], v[150:153], v[196:199], v[80:83]
	v_mfma_f32_16x16x32_bf16 v[76:79], v[138:141], v[204:207], v[76:79]
	v_mfma_f32_16x16x32_bf16 v[64:67], v[150:153], v[204:207], v[64:67]
	v_mfma_f32_16x16x32_bf16 v[124:127], v[146:149], v[182:185], v[124:127]
	v_mfma_f32_16x16x32_bf16 v[112:115], v[154:157], v[182:185], v[112:115]
	v_mfma_f32_16x16x32_bf16 v[108:111], v[146:149], v[192:195], v[108:111]
	v_mfma_f32_16x16x32_bf16 v[96:99], v[154:157], v[192:195], v[96:99]
	v_mfma_f32_16x16x32_bf16 v[92:95], v[146:149], v[200:203], v[92:95]
	v_mfma_f32_16x16x32_bf16 v[80:83], v[154:157], v[200:203], v[80:83]
	v_mfma_f32_16x16x32_bf16 v[76:79], v[146:149], v[208:211], v[76:79]
	v_mfma_f32_16x16x32_bf16 v[64:67], v[154:157], v[208:211], v[64:67]
	s_setprio 0
	s_setprio 1
	v_mfma_f32_16x16x32_bf16 v[120:123], v[158:161], v[178:181], v[120:123]
	v_mfma_f32_16x16x32_bf16 v[116:119], v[166:169], v[178:181], v[116:119]
	v_mfma_f32_16x16x32_bf16 v[104:107], v[158:161], v[188:191], v[104:107]
	v_mfma_f32_16x16x32_bf16 v[100:103], v[166:169], v[188:191], v[100:103]
	v_mfma_f32_16x16x32_bf16 v[88:91], v[158:161], v[196:199], v[88:91]
	v_mfma_f32_16x16x32_bf16 v[84:87], v[166:169], v[196:199], v[84:87]
	v_mfma_f32_16x16x32_bf16 v[72:75], v[158:161], v[204:207], v[72:75]
	v_mfma_f32_16x16x32_bf16 v[68:71], v[166:169], v[204:207], v[68:71]
	v_mfma_f32_16x16x32_bf16 v[120:123], v[162:165], v[182:185], v[120:123]
	v_mfma_f32_16x16x32_bf16 v[116:119], v[170:173], v[182:185], v[116:119]
	v_mfma_f32_16x16x32_bf16 v[104:107], v[162:165], v[192:195], v[104:107]
	v_mfma_f32_16x16x32_bf16 v[100:103], v[170:173], v[192:195], v[100:103]
	v_mfma_f32_16x16x32_bf16 v[88:91], v[162:165], v[200:203], v[88:91]
	v_mfma_f32_16x16x32_bf16 v[84:87], v[170:173], v[200:203], v[84:87]
	v_mfma_f32_16x16x32_bf16 v[72:75], v[162:165], v[208:211], v[72:75]
	v_mfma_f32_16x16x32_bf16 v[68:71], v[170:173], v[208:211], v[68:71]
	s_setprio 0
	s_barrier
	s_add_i32 s38, s38, s44
	s_add_u32 s90, s34, 0x80
	s_addc_u32 s91, s35, 0
	s_mov_b32 m0, s38
	ds_read_b128 v[178:181], v145 offset:16384
	ds_read_b128 v[182:185], v145 offset:17408
	ds_read_b128 v[188:191], v145 offset:18432
	ds_read_b128 v[192:195], v145 offset:19456
	ds_read_b128 v[196:199], v145 offset:20480
	ds_read_b128 v[200:203], v145 offset:21504
	ds_read_b128 v[204:207], v145 offset:22528
	ds_read_b128 v[208:211], v145 offset:23552
	global_load_lds_dwordx4 v176, s[34:35]
	s_add_i32 m0, s38, 0x2000
	s_add_u32 s80, s34, 0x40000
	s_addc_u32 s81, s35, 0
	s_add_i32 s38, s39, s44
	global_load_lds_dwordx4 v132, s[34:35]
	s_mov_b32 m0, s38
	s_nop 0
	global_load_lds_dwordx4 v176, s[80:81]
	s_add_i32 m0, s38, 0x2000
	s_nop 0
	global_load_lds_dwordx4 v132, s[80:81]
	s_add_u32 s98, s48, 0x80
	s_addc_u32 s99, s49, 0
	s_mov_b32 m0, s10
	s_nop 0
	global_load_lds_dwordx4 v128, s[48:49]
	s_mov_b32 m0, s11
	s_nop 0
	global_load_lds_dwordx4 v130, s[48:49]
	s_waitcnt vmcnt(8)
	s_waitcnt lgkmcnt(0)
	s_barrier
	s_setprio 1
	s_waitcnt lgkmcnt(0)
	v_mfma_f32_16x16x32_bf16 v[60:63], v[138:141], v[178:181], v[60:63]
	v_mfma_f32_16x16x32_bf16 v[48:51], v[150:153], v[178:181], v[48:51]
	v_mfma_f32_16x16x32_bf16 v[44:47], v[138:141], v[188:191], v[44:47]
	v_mfma_f32_16x16x32_bf16 v[32:35], v[150:153], v[188:191], v[32:35]
	v_mfma_f32_16x16x32_bf16 v[28:31], v[138:141], v[196:199], v[28:31]
	v_mfma_f32_16x16x32_bf16 v[16:19], v[150:153], v[196:199], v[16:19]
	v_mfma_f32_16x16x32_bf16 v[12:15], v[138:141], v[204:207], v[12:15]
	v_mfma_f32_16x16x32_bf16 v[8:11], v[150:153], v[204:207], v[8:11]
	v_mfma_f32_16x16x32_bf16 v[60:63], v[146:149], v[182:185], v[60:63]
	v_mfma_f32_16x16x32_bf16 v[48:51], v[154:157], v[182:185], v[48:51]
	v_mfma_f32_16x16x32_bf16 v[44:47], v[146:149], v[192:195], v[44:47]
	v_mfma_f32_16x16x32_bf16 v[32:35], v[154:157], v[192:195], v[32:35]
	v_mfma_f32_16x16x32_bf16 v[28:31], v[146:149], v[200:203], v[28:31]
	v_mfma_f32_16x16x32_bf16 v[16:19], v[154:157], v[200:203], v[16:19]
	v_mfma_f32_16x16x32_bf16 v[12:15], v[146:149], v[208:211], v[12:15]
	v_mfma_f32_16x16x32_bf16 v[8:11], v[154:157], v[208:211], v[8:11]
	s_setprio 0
	s_setprio 1
	v_mfma_f32_16x16x32_bf16 v[56:59], v[158:161], v[178:181], v[56:59]
	v_mfma_f32_16x16x32_bf16 v[52:55], v[166:169], v[178:181], v[52:55]
	v_mfma_f32_16x16x32_bf16 v[40:43], v[158:161], v[188:191], v[40:43]
	v_mfma_f32_16x16x32_bf16 v[36:39], v[166:169], v[188:191], v[36:39]
	v_mfma_f32_16x16x32_bf16 v[24:27], v[158:161], v[196:199], v[24:27]
	v_mfma_f32_16x16x32_bf16 v[20:23], v[166:169], v[196:199], v[20:23]
	v_mfma_f32_16x16x32_bf16 v[4:7], v[158:161], v[204:207], v[4:7]
	v_mfma_f32_16x16x32_bf16 v[0:3], v[166:169], v[204:207], v[0:3]
	v_mfma_f32_16x16x32_bf16 v[56:59], v[162:165], v[182:185], v[56:59]
	v_mfma_f32_16x16x32_bf16 v[52:55], v[170:173], v[182:185], v[52:55]
	v_mfma_f32_16x16x32_bf16 v[40:43], v[162:165], v[192:195], v[40:43]
	v_mfma_f32_16x16x32_bf16 v[36:39], v[170:173], v[192:195], v[36:39]
	v_mfma_f32_16x16x32_bf16 v[24:27], v[162:165], v[200:203], v[24:27]
	v_mfma_f32_16x16x32_bf16 v[20:23], v[170:173], v[200:203], v[20:23]
	v_mfma_f32_16x16x32_bf16 v[4:7], v[162:165], v[208:211], v[4:7]
	v_mfma_f32_16x16x32_bf16 v[0:3], v[170:173], v[208:211], v[0:3]
	s_setprio 0
	s_barrier
	s_add_i32 s38, 0, 0x18000
	s_add_i32 s39, 0, 0x1c000
	v_add_u32_e32 v154, s38, v144
	v_add_u32_e32 v170, s39, v144
	ds_read_b128 v[138:141], v154
	ds_read_b128 v[146:149], v154 offset:1024
	ds_read_b128 v[150:153], v154 offset:2048
	ds_read_b128 v[154:157], v154 offset:3072
	ds_read_b128 v[158:161], v170
	ds_read_b128 v[162:165], v170 offset:1024
	ds_read_b128 v[166:169], v170 offset:2048
	ds_read_b128 v[170:173], v170 offset:3072
	s_add_u32 s48, s48, 0x40000
	s_addc_u32 s49, s49, 0
	s_mov_b32 m0, s8
	ds_read_b128 v[178:181], v145 offset:32768
	ds_read_b128 v[182:185], v145 offset:33792
	ds_read_b128 v[188:191], v145 offset:34816
	ds_read_b128 v[192:195], v145 offset:35840
	ds_read_b128 v[196:199], v145 offset:36864
	ds_read_b128 v[200:203], v145 offset:37888
	ds_read_b128 v[204:207], v145 offset:38912
	ds_read_b128 v[208:211], v145 offset:39936
	global_load_lds_dwordx4 v128, s[48:49]
	s_mov_b32 m0, s9
	s_nop 0
	global_load_lds_dwordx4 v130, s[48:49]
	s_waitcnt vmcnt(8)
	s_waitcnt lgkmcnt(0)
	s_barrier
	s_setprio 1
	s_waitcnt lgkmcnt(0)
	v_mfma_f32_16x16x32_bf16 v[124:127], v[138:141], v[178:181], v[124:127]
	v_mfma_f32_16x16x32_bf16 v[112:115], v[150:153], v[178:181], v[112:115]
	v_mfma_f32_16x16x32_bf16 v[108:111], v[138:141], v[188:191], v[108:111]
	v_mfma_f32_16x16x32_bf16 v[96:99], v[150:153], v[188:191], v[96:99]
	v_mfma_f32_16x16x32_bf16 v[92:95], v[138:141], v[196:199], v[92:95]
	v_mfma_f32_16x16x32_bf16 v[80:83], v[150:153], v[196:199], v[80:83]
	v_mfma_f32_16x16x32_bf16 v[76:79], v[138:141], v[204:207], v[76:79]
	v_mfma_f32_16x16x32_bf16 v[64:67], v[150:153], v[204:207], v[64:67]
	v_mfma_f32_16x16x32_bf16 v[124:127], v[146:149], v[182:185], v[124:127]
	v_mfma_f32_16x16x32_bf16 v[112:115], v[154:157], v[182:185], v[112:115]
	v_mfma_f32_16x16x32_bf16 v[108:111], v[146:149], v[192:195], v[108:111]
	v_mfma_f32_16x16x32_bf16 v[96:99], v[154:157], v[192:195], v[96:99]
	v_mfma_f32_16x16x32_bf16 v[92:95], v[146:149], v[200:203], v[92:95]
	v_mfma_f32_16x16x32_bf16 v[80:83], v[154:157], v[200:203], v[80:83]
	v_mfma_f32_16x16x32_bf16 v[76:79], v[146:149], v[208:211], v[76:79]
	v_mfma_f32_16x16x32_bf16 v[64:67], v[154:157], v[208:211], v[64:67]
	s_setprio 0
	s_setprio 1
	v_mfma_f32_16x16x32_bf16 v[120:123], v[158:161], v[178:181], v[120:123]
	v_mfma_f32_16x16x32_bf16 v[116:119], v[166:169], v[178:181], v[116:119]
	v_mfma_f32_16x16x32_bf16 v[104:107], v[158:161], v[188:191], v[104:107]
	v_mfma_f32_16x16x32_bf16 v[100:103], v[166:169], v[188:191], v[100:103]
	v_mfma_f32_16x16x32_bf16 v[88:91], v[158:161], v[196:199], v[88:91]
	v_mfma_f32_16x16x32_bf16 v[84:87], v[166:169], v[196:199], v[84:87]
	v_mfma_f32_16x16x32_bf16 v[72:75], v[158:161], v[204:207], v[72:75]
	v_mfma_f32_16x16x32_bf16 v[68:71], v[166:169], v[204:207], v[68:71]
	v_mfma_f32_16x16x32_bf16 v[120:123], v[162:165], v[182:185], v[120:123]
	v_mfma_f32_16x16x32_bf16 v[116:119], v[170:173], v[182:185], v[116:119]
	v_mfma_f32_16x16x32_bf16 v[104:107], v[162:165], v[192:195], v[104:107]
	v_mfma_f32_16x16x32_bf16 v[100:103], v[170:173], v[192:195], v[100:103]
	v_mfma_f32_16x16x32_bf16 v[88:91], v[162:165], v[200:203], v[88:91]
	v_mfma_f32_16x16x32_bf16 v[84:87], v[170:173], v[200:203], v[84:87]
	v_mfma_f32_16x16x32_bf16 v[72:75], v[162:165], v[208:211], v[72:75]
	v_mfma_f32_16x16x32_bf16 v[68:71], v[170:173], v[208:211], v[68:71]
	s_setprio 0
	s_barrier
	s_add_i32 s38, s38, s44
	s_mov_b32 m0, s38
	ds_read_b128 v[178:181], v145 offset:49152
	ds_read_b128 v[182:185], v145 offset:50176
	ds_read_b128 v[188:191], v145 offset:51200
	ds_read_b128 v[192:195], v145 offset:52224
	ds_read_b128 v[196:199], v145 offset:53248
	ds_read_b128 v[200:203], v145 offset:54272
	ds_read_b128 v[204:207], v145 offset:55296
	ds_read_b128 v[208:211], v145 offset:56320
	global_load_lds_dwordx4 v176, s[90:91]
	s_add_i32 m0, s38, 0x2000
	s_add_u32 s34, s34, 0x40080
	s_addc_u32 s35, s35, 0
	s_add_i32 s38, s39, s44
	global_load_lds_dwordx4 v132, s[90:91]
	s_mov_b32 m0, s38
	s_nop 0
	global_load_lds_dwordx4 v176, s[34:35]
	s_add_i32 m0, s38, 0x2000
	s_nop 0
	global_load_lds_dwordx4 v132, s[34:35]
	s_mov_b32 m0, s93
	s_nop 0
	global_load_lds_dwordx4 v128, s[98:99]
	s_mov_b32 m0, s85
	s_nop 0
	global_load_lds_dwordx4 v130, s[98:99]
	s_waitcnt vmcnt(8)
	s_waitcnt lgkmcnt(0)
	s_barrier
	s_setprio 1
	s_waitcnt lgkmcnt(0)
	v_mfma_f32_16x16x32_bf16 v[60:63], v[138:141], v[178:181], v[60:63]
	v_mfma_f32_16x16x32_bf16 v[48:51], v[150:153], v[178:181], v[48:51]
	v_mfma_f32_16x16x32_bf16 v[44:47], v[138:141], v[188:191], v[44:47]
	v_mfma_f32_16x16x32_bf16 v[32:35], v[150:153], v[188:191], v[32:35]
	v_mfma_f32_16x16x32_bf16 v[28:31], v[138:141], v[196:199], v[28:31]
	v_mfma_f32_16x16x32_bf16 v[16:19], v[150:153], v[196:199], v[16:19]
	v_mfma_f32_16x16x32_bf16 v[12:15], v[138:141], v[204:207], v[12:15]
	v_mfma_f32_16x16x32_bf16 v[8:11], v[150:153], v[204:207], v[8:11]
	v_mfma_f32_16x16x32_bf16 v[60:63], v[146:149], v[182:185], v[60:63]
	v_mfma_f32_16x16x32_bf16 v[48:51], v[154:157], v[182:185], v[48:51]
	v_mfma_f32_16x16x32_bf16 v[44:47], v[146:149], v[192:195], v[44:47]
	v_mfma_f32_16x16x32_bf16 v[32:35], v[154:157], v[192:195], v[32:35]
	v_mfma_f32_16x16x32_bf16 v[28:31], v[146:149], v[200:203], v[28:31]
	v_mfma_f32_16x16x32_bf16 v[16:19], v[154:157], v[200:203], v[16:19]
	v_mfma_f32_16x16x32_bf16 v[12:15], v[146:149], v[208:211], v[12:15]
	v_mfma_f32_16x16x32_bf16 v[8:11], v[154:157], v[208:211], v[8:11]
	s_setprio 0
	s_setprio 1
	v_mfma_f32_16x16x32_bf16 v[56:59], v[158:161], v[178:181], v[56:59]
	v_mfma_f32_16x16x32_bf16 v[52:55], v[166:169], v[178:181], v[52:55]
	v_mfma_f32_16x16x32_bf16 v[40:43], v[158:161], v[188:191], v[40:43]
	v_mfma_f32_16x16x32_bf16 v[36:39], v[166:169], v[188:191], v[36:39]
	v_mfma_f32_16x16x32_bf16 v[24:27], v[158:161], v[196:199], v[24:27]
	v_mfma_f32_16x16x32_bf16 v[20:23], v[166:169], v[196:199], v[20:23]
	v_mfma_f32_16x16x32_bf16 v[4:7], v[158:161], v[204:207], v[4:7]
	v_mfma_f32_16x16x32_bf16 v[0:3], v[166:169], v[204:207], v[0:3]
	v_mfma_f32_16x16x32_bf16 v[56:59], v[162:165], v[182:185], v[56:59]
	v_mfma_f32_16x16x32_bf16 v[52:55], v[170:173], v[182:185], v[52:55]
	v_mfma_f32_16x16x32_bf16 v[40:43], v[162:165], v[192:195], v[40:43]
	v_mfma_f32_16x16x32_bf16 v[36:39], v[170:173], v[192:195], v[36:39]
	v_mfma_f32_16x16x32_bf16 v[24:27], v[162:165], v[200:203], v[24:27]
	v_mfma_f32_16x16x32_bf16 v[20:23], v[170:173], v[200:203], v[20:23]
	v_mfma_f32_16x16x32_bf16 v[4:7], v[162:165], v[208:211], v[4:7]
	v_mfma_f32_16x16x32_bf16 v[0:3], v[170:173], v[208:211], v[0:3]
	s_setprio 0
	s_barrier
	s_add_i32 s79, s79, 2
	s_add_u32 s30, s30, 0x100
	s_addc_u32 s31, s31, 0
	s_add_u32 s55, s55, 0x100
	s_addc_u32 s78, s78, 0
	s_cmp_gt_u32 s79, 13
	s_cbranch_scc0 .LBB0_761
	s_and_b64 vcc, exec, s[18:19]
	s_cbranch_vccz .LBB0_764
	s_barrier

.LBB0_841:
	s_add_u32 s28, s26, 0x100
	s_addc_u32 s29, s27, 0
	s_add_i32 s38, 0, 0x10000
	s_cmp_eq_u32 s81, 14
	s_cselect_b32 s35, s23, s29
	s_cselect_b32 s34, s22, s28
	s_cselect_b32 s31, s25, s80
	s_cselect_b32 s30, s24, s79
	s_add_i32 s39, 0, 0x14000
	v_add_u32_e32 v152, s38, v146
	v_add_u32_e32 v168, s39, v146
	ds_read_b128 v[138:141], v152
	ds_read_b128 v[142:145], v152 offset:1024
	ds_read_b128 v[148:151], v152 offset:2048
	ds_read_b128 v[152:155], v152 offset:3072
	ds_read_b128 v[156:159], v168
	ds_read_b128 v[160:163], v168 offset:1024
	ds_read_b128 v[164:167], v168 offset:2048
	ds_read_b128 v[168:171], v168 offset:3072
	s_add_i32 m0, s50, 0xc000
	ds_read_b128 v[172:175], v147
	ds_read_b128 v[178:181], v147 offset:1024
	ds_read_b128 v[182:185], v147 offset:2048
	ds_read_b128 v[188:191], v147 offset:3072
	ds_read_b128 v[192:195], v147 offset:4096
	ds_read_b128 v[196:199], v147 offset:5120
	ds_read_b128 v[200:203], v147 offset:6144
	ds_read_b128 v[204:207], v147 offset:7168
	global_load_lds_dwordx4 v134, s[26:27]
	s_add_i32 m0, s50, 0xe000
	s_nop 0
	global_load_lds_dwordx4 v136, s[26:27]
	s_waitcnt vmcnt(8)
	s_waitcnt lgkmcnt(0)
	s_barrier
	s_setprio 1
	s_waitcnt lgkmcnt(0)
	v_mfma_f32_16x16x32_bf16 v[124:127], v[138:141], v[172:175], v[124:127]
	v_mfma_f32_16x16x32_bf16 v[120:123], v[148:151], v[172:175], v[120:123]
	v_mfma_f32_16x16x32_bf16 v[108:111], v[138:141], v[182:185], v[108:111]
	v_mfma_f32_16x16x32_bf16 v[104:107], v[148:151], v[182:185], v[104:107]
	v_mfma_f32_16x16x32_bf16 v[92:95], v[138:141], v[192:195], v[92:95]
	v_mfma_f32_16x16x32_bf16 v[88:91], v[148:151], v[192:195], v[88:91]
	v_mfma_f32_16x16x32_bf16 v[76:79], v[138:141], v[200:203], v[76:79]
	v_mfma_f32_16x16x32_bf16 v[72:75], v[148:151], v[200:203], v[72:75]
	v_mfma_f32_16x16x32_bf16 v[124:127], v[142:145], v[178:181], v[124:127]
	v_mfma_f32_16x16x32_bf16 v[120:123], v[152:155], v[178:181], v[120:123]
	v_mfma_f32_16x16x32_bf16 v[108:111], v[142:145], v[188:191], v[108:111]
	v_mfma_f32_16x16x32_bf16 v[104:107], v[152:155], v[188:191], v[104:107]
	v_mfma_f32_16x16x32_bf16 v[92:95], v[142:145], v[196:199], v[92:95]
	v_mfma_f32_16x16x32_bf16 v[88:91], v[152:155], v[196:199], v[88:91]
	v_mfma_f32_16x16x32_bf16 v[76:79], v[142:145], v[204:207], v[76:79]
	v_mfma_f32_16x16x32_bf16 v[72:75], v[152:155], v[204:207], v[72:75]
	s_setprio 0
	s_setprio 1
	v_mfma_f32_16x16x32_bf16 v[116:119], v[156:159], v[172:175], v[116:119]
	v_mfma_f32_16x16x32_bf16 v[112:115], v[164:167], v[172:175], v[112:115]
	v_mfma_f32_16x16x32_bf16 v[100:103], v[156:159], v[182:185], v[100:103]
	v_mfma_f32_16x16x32_bf16 v[96:99], v[164:167], v[182:185], v[96:99]
	v_mfma_f32_16x16x32_bf16 v[84:87], v[156:159], v[192:195], v[84:87]
	v_mfma_f32_16x16x32_bf16 v[80:83], v[164:167], v[192:195], v[80:83]
	v_mfma_f32_16x16x32_bf16 v[68:71], v[156:159], v[200:203], v[68:71]
	v_mfma_f32_16x16x32_bf16 v[64:67], v[164:167], v[200:203], v[64:67]
	v_mfma_f32_16x16x32_bf16 v[116:119], v[160:163], v[178:181], v[116:119]
	v_mfma_f32_16x16x32_bf16 v[112:115], v[168:171], v[178:181], v[112:115]
	v_mfma_f32_16x16x32_bf16 v[100:103], v[160:163], v[188:191], v[100:103]
	v_mfma_f32_16x16x32_bf16 v[96:99], v[168:171], v[188:191], v[96:99]
	v_mfma_f32_16x16x32_bf16 v[84:87], v[160:163], v[196:199], v[84:87]
	v_mfma_f32_16x16x32_bf16 v[80:83], v[168:171], v[196:199], v[80:83]
	v_mfma_f32_16x16x32_bf16 v[68:71], v[160:163], v[204:207], v[68:71]
	v_mfma_f32_16x16x32_bf16 v[64:67], v[168:171], v[204:207], v[64:67]
	s_setprio 0
	s_barrier
	s_add_i32 s26, s38, s49
	s_add_u32 s90, s30, 0x80
	s_addc_u32 s91, s31, 0
	s_mov_b32 m0, s26
	ds_read_b128 v[172:175], v147 offset:16384
	ds_read_b128 v[178:181], v147 offset:17408
	ds_read_b128 v[182:185], v147 offset:18432
	ds_read_b128 v[188:191], v147 offset:19456
	ds_read_b128 v[192:195], v147 offset:20480
	ds_read_b128 v[196:199], v147 offset:21504
	ds_read_b128 v[200:203], v147 offset:22528
	ds_read_b128 v[204:207], v147 offset:23552
	global_load_lds_dwordx4 v176, s[30:31]
	s_add_i32 m0, s26, 0x2000
	s_add_u32 s26, s30, 0x48000
	s_addc_u32 s27, s31, 0
	s_add_i32 s38, s39, s49
	global_load_lds_dwordx4 v132, s[30:31]
	s_mov_b32 m0, s38
	s_nop 0
	global_load_lds_dwordx4 v176, s[26:27]
	s_add_i32 m0, s38, 0x2000
	s_nop 0
	global_load_lds_dwordx4 v132, s[26:27]
	s_add_u32 s96, s34, 0x80
	s_addc_u32 s97, s35, 0
	s_mov_b32 m0, s50
	s_nop 0
	global_load_lds_dwordx4 v128, s[34:35]
	s_mov_b32 m0, s51
	s_nop 0
	global_load_lds_dwordx4 v130, s[34:35]
	s_waitcnt vmcnt(8)
	s_waitcnt lgkmcnt(0)
	s_barrier
	s_setprio 1
	s_waitcnt lgkmcnt(0)
	v_mfma_f32_16x16x32_bf16 v[60:63], v[138:141], v[172:175], v[60:63]
	v_mfma_f32_16x16x32_bf16 v[56:59], v[148:151], v[172:175], v[56:59]
	v_mfma_f32_16x16x32_bf16 v[44:47], v[138:141], v[182:185], v[44:47]
	v_mfma_f32_16x16x32_bf16 v[40:43], v[148:151], v[182:185], v[40:43]
	v_mfma_f32_16x16x32_bf16 v[28:31], v[138:141], v[192:195], v[28:31]
	v_mfma_f32_16x16x32_bf16 v[24:27], v[148:151], v[192:195], v[24:27]
	v_mfma_f32_16x16x32_bf16 v[12:15], v[138:141], v[200:203], v[12:15]
	v_mfma_f32_16x16x32_bf16 v[8:11], v[148:151], v[200:203], v[8:11]
	v_mfma_f32_16x16x32_bf16 v[60:63], v[142:145], v[178:181], v[60:63]
	v_mfma_f32_16x16x32_bf16 v[56:59], v[152:155], v[178:181], v[56:59]
	v_mfma_f32_16x16x32_bf16 v[44:47], v[142:145], v[188:191], v[44:47]
	v_mfma_f32_16x16x32_bf16 v[40:43], v[152:155], v[188:191], v[40:43]
	v_mfma_f32_16x16x32_bf16 v[28:31], v[142:145], v[196:199], v[28:31]
	v_mfma_f32_16x16x32_bf16 v[24:27], v[152:155], v[196:199], v[24:27]
	v_mfma_f32_16x16x32_bf16 v[12:15], v[142:145], v[204:207], v[12:15]
	v_mfma_f32_16x16x32_bf16 v[8:11], v[152:155], v[204:207], v[8:11]
	s_setprio 0
	s_setprio 1
	v_mfma_f32_16x16x32_bf16 v[52:55], v[156:159], v[172:175], v[52:55]
	v_mfma_f32_16x16x32_bf16 v[48:51], v[164:167], v[172:175], v[48:51]
	v_mfma_f32_16x16x32_bf16 v[36:39], v[156:159], v[182:185], v[36:39]
	v_mfma_f32_16x16x32_bf16 v[32:35], v[164:167], v[182:185], v[32:35]
	v_mfma_f32_16x16x32_bf16 v[20:23], v[156:159], v[192:195], v[20:23]
	v_mfma_f32_16x16x32_bf16 v[16:19], v[164:167], v[192:195], v[16:19]
	v_mfma_f32_16x16x32_bf16 v[4:7], v[156:159], v[200:203], v[4:7]
	v_mfma_f32_16x16x32_bf16 v[0:3], v[164:167], v[200:203], v[0:3]
	v_mfma_f32_16x16x32_bf16 v[52:55], v[160:163], v[178:181], v[52:55]
	v_mfma_f32_16x16x32_bf16 v[48:51], v[168:171], v[178:181], v[48:51]
	v_mfma_f32_16x16x32_bf16 v[36:39], v[160:163], v[188:191], v[36:39]
	v_mfma_f32_16x16x32_bf16 v[32:35], v[168:171], v[188:191], v[32:35]
	v_mfma_f32_16x16x32_bf16 v[20:23], v[160:163], v[196:199], v[20:23]
	v_mfma_f32_16x16x32_bf16 v[16:19], v[168:171], v[196:199], v[16:19]
	v_mfma_f32_16x16x32_bf16 v[4:7], v[160:163], v[204:207], v[4:7]
	v_mfma_f32_16x16x32_bf16 v[0:3], v[168:171], v[204:207], v[0:3]
	s_setprio 0
	s_barrier
	s_add_i32 s38, 0, 0x18000
	s_add_i32 s39, 0, 0x1c000
	v_add_u32_e32 v152, s38, v146
	v_add_u32_e32 v168, s39, v146
	ds_read_b128 v[138:141], v152
	ds_read_b128 v[142:145], v152 offset:1024
	ds_read_b128 v[148:151], v152 offset:2048
	ds_read_b128 v[152:155], v152 offset:3072
	ds_read_b128 v[156:159], v168
	ds_read_b128 v[160:163], v168 offset:1024
	ds_read_b128 v[164:167], v168 offset:2048
	ds_read_b128 v[168:171], v168 offset:3072
	s_add_u32 s26, s34, 0x48000
	s_addc_u32 s27, s35, 0
	s_mov_b32 m0, s52
	ds_read_b128 v[172:175], v147 offset:32768
	ds_read_b128 v[178:181], v147 offset:33792
	ds_read_b128 v[182:185], v147 offset:34816
	ds_read_b128 v[188:191], v147 offset:35840
	ds_read_b128 v[192:195], v147 offset:36864
	ds_read_b128 v[196:199], v147 offset:37888
	ds_read_b128 v[200:203], v147 offset:38912
	ds_read_b128 v[204:207], v147 offset:39936
	global_load_lds_dwordx4 v128, s[26:27]
	s_mov_b32 m0, s56
	s_nop 0
	global_load_lds_dwordx4 v130, s[26:27]
	s_waitcnt vmcnt(8)
	s_waitcnt lgkmcnt(0)
	s_barrier
	s_setprio 1
	s_waitcnt lgkmcnt(0)
	v_mfma_f32_16x16x32_bf16 v[124:127], v[138:141], v[172:175], v[124:127]
	v_mfma_f32_16x16x32_bf16 v[120:123], v[148:151], v[172:175], v[120:123]
	v_mfma_f32_16x16x32_bf16 v[108:111], v[138:141], v[182:185], v[108:111]
	v_mfma_f32_16x16x32_bf16 v[104:107], v[148:151], v[182:185], v[104:107]
	v_mfma_f32_16x16x32_bf16 v[92:95], v[138:141], v[192:195], v[92:95]
	v_mfma_f32_16x16x32_bf16 v[88:91], v[148:151], v[192:195], v[88:91]
	v_mfma_f32_16x16x32_bf16 v[76:79], v[138:141], v[200:203], v[76:79]
	v_mfma_f32_16x16x32_bf16 v[72:75], v[148:151], v[200:203], v[72:75]
	v_mfma_f32_16x16x32_bf16 v[124:127], v[142:145], v[178:181], v[124:127]
	v_mfma_f32_16x16x32_bf16 v[120:123], v[152:155], v[178:181], v[120:123]
	v_mfma_f32_16x16x32_bf16 v[108:111], v[142:145], v[188:191], v[108:111]
	v_mfma_f32_16x16x32_bf16 v[104:107], v[152:155], v[188:191], v[104:107]
	v_mfma_f32_16x16x32_bf16 v[92:95], v[142:145], v[196:199], v[92:95]
	v_mfma_f32_16x16x32_bf16 v[88:91], v[152:155], v[196:199], v[88:91]
	v_mfma_f32_16x16x32_bf16 v[76:79], v[142:145], v[204:207], v[76:79]
	v_mfma_f32_16x16x32_bf16 v[72:75], v[152:155], v[204:207], v[72:75]
	s_setprio 0
	s_setprio 1
	v_mfma_f32_16x16x32_bf16 v[116:119], v[156:159], v[172:175], v[116:119]
	v_mfma_f32_16x16x32_bf16 v[112:115], v[164:167], v[172:175], v[112:115]
	v_mfma_f32_16x16x32_bf16 v[100:103], v[156:159], v[182:185], v[100:103]
	v_mfma_f32_16x16x32_bf16 v[96:99], v[164:167], v[182:185], v[96:99]
	v_mfma_f32_16x16x32_bf16 v[84:87], v[156:159], v[192:195], v[84:87]
	v_mfma_f32_16x16x32_bf16 v[80:83], v[164:167], v[192:195], v[80:83]
	v_mfma_f32_16x16x32_bf16 v[68:71], v[156:159], v[200:203], v[68:71]
	v_mfma_f32_16x16x32_bf16 v[64:67], v[164:167], v[200:203], v[64:67]
	v_mfma_f32_16x16x32_bf16 v[116:119], v[160:163], v[178:181], v[116:119]
	v_mfma_f32_16x16x32_bf16 v[112:115], v[168:171], v[178:181], v[112:115]
	v_mfma_f32_16x16x32_bf16 v[100:103], v[160:163], v[188:191], v[100:103]
	v_mfma_f32_16x16x32_bf16 v[96:99], v[168:171], v[188:191], v[96:99]
	v_mfma_f32_16x16x32_bf16 v[84:87], v[160:163], v[196:199], v[84:87]
	v_mfma_f32_16x16x32_bf16 v[80:83], v[168:171], v[196:199], v[80:83]
	v_mfma_f32_16x16x32_bf16 v[68:71], v[160:163], v[204:207], v[68:71]
	v_mfma_f32_16x16x32_bf16 v[64:67], v[168:171], v[204:207], v[64:67]
	s_setprio 0
	s_barrier
	s_add_i32 s26, s38, s49
	s_mov_b32 m0, s26
	ds_read_b128 v[172:175], v147 offset:49152
	ds_read_b128 v[178:181], v147 offset:50176
	ds_read_b128 v[182:185], v147 offset:51200
	ds_read_b128 v[188:191], v147 offset:52224
	ds_read_b128 v[192:195], v147 offset:53248
	ds_read_b128 v[196:199], v147 offset:54272
	ds_read_b128 v[200:203], v147 offset:55296
	ds_read_b128 v[204:207], v147 offset:56320
	global_load_lds_dwordx4 v176, s[90:91]
	s_add_i32 m0, s26, 0x2000
	s_add_u32 s26, s30, 0x48080
	s_addc_u32 s27, s31, 0
	s_add_i32 s30, s39, s49
	global_load_lds_dwordx4 v132, s[90:91]
	s_mov_b32 m0, s30
	s_nop 0
	global_load_lds_dwordx4 v176, s[26:27]
	s_add_i32 m0, s30, 0x2000
	s_nop 0
	global_load_lds_dwordx4 v132, s[26:27]
	s_mov_b32 m0, s57
	s_nop 0
	global_load_lds_dwordx4 v128, s[96:97]
	s_mov_b32 m0, s85
	s_nop 0
	global_load_lds_dwordx4 v130, s[96:97]
	s_waitcnt vmcnt(8)
	s_waitcnt lgkmcnt(0)
	s_barrier
	s_setprio 1
	s_waitcnt lgkmcnt(0)
	v_mfma_f32_16x16x32_bf16 v[60:63], v[138:141], v[172:175], v[60:63]
	v_mfma_f32_16x16x32_bf16 v[56:59], v[148:151], v[172:175], v[56:59]
	v_mfma_f32_16x16x32_bf16 v[44:47], v[138:141], v[182:185], v[44:47]
	v_mfma_f32_16x16x32_bf16 v[40:43], v[148:151], v[182:185], v[40:43]
	v_mfma_f32_16x16x32_bf16 v[28:31], v[138:141], v[192:195], v[28:31]
	v_mfma_f32_16x16x32_bf16 v[24:27], v[148:151], v[192:195], v[24:27]
	v_mfma_f32_16x16x32_bf16 v[12:15], v[138:141], v[200:203], v[12:15]
	v_mfma_f32_16x16x32_bf16 v[8:11], v[148:151], v[200:203], v[8:11]
	v_mfma_f32_16x16x32_bf16 v[60:63], v[142:145], v[178:181], v[60:63]
	v_mfma_f32_16x16x32_bf16 v[56:59], v[152:155], v[178:181], v[56:59]
	v_mfma_f32_16x16x32_bf16 v[44:47], v[142:145], v[188:191], v[44:47]
	v_mfma_f32_16x16x32_bf16 v[40:43], v[152:155], v[188:191], v[40:43]
	v_mfma_f32_16x16x32_bf16 v[28:31], v[142:145], v[196:199], v[28:31]
	v_mfma_f32_16x16x32_bf16 v[24:27], v[152:155], v[196:199], v[24:27]
	v_mfma_f32_16x16x32_bf16 v[12:15], v[142:145], v[204:207], v[12:15]
	v_mfma_f32_16x16x32_bf16 v[8:11], v[152:155], v[204:207], v[8:11]
	s_setprio 0
	s_setprio 1
	v_mfma_f32_16x16x32_bf16 v[52:55], v[156:159], v[172:175], v[52:55]
	v_mfma_f32_16x16x32_bf16 v[48:51], v[164:167], v[172:175], v[48:51]
	v_mfma_f32_16x16x32_bf16 v[36:39], v[156:159], v[182:185], v[36:39]
	v_mfma_f32_16x16x32_bf16 v[32:35], v[164:167], v[182:185], v[32:35]
	v_mfma_f32_16x16x32_bf16 v[20:23], v[156:159], v[192:195], v[20:23]
	v_mfma_f32_16x16x32_bf16 v[16:19], v[164:167], v[192:195], v[16:19]
	v_mfma_f32_16x16x32_bf16 v[4:7], v[156:159], v[200:203], v[4:7]
	v_mfma_f32_16x16x32_bf16 v[0:3], v[164:167], v[200:203], v[0:3]
	v_mfma_f32_16x16x32_bf16 v[52:55], v[160:163], v[178:181], v[52:55]
	v_mfma_f32_16x16x32_bf16 v[48:51], v[168:171], v[178:181], v[48:51]
	v_mfma_f32_16x16x32_bf16 v[36:39], v[160:163], v[188:191], v[36:39]
	v_mfma_f32_16x16x32_bf16 v[32:35], v[168:171], v[188:191], v[32:35]
	v_mfma_f32_16x16x32_bf16 v[20:23], v[160:163], v[196:199], v[20:23]
	v_mfma_f32_16x16x32_bf16 v[16:19], v[168:171], v[196:199], v[16:19]
	v_mfma_f32_16x16x32_bf16 v[4:7], v[160:163], v[204:207], v[4:7]
	v_mfma_f32_16x16x32_bf16 v[0:3], v[168:171], v[204:207], v[0:3]
	s_setprio 0
	s_barrier
	s_add_i32 s81, s81, 2
	s_add_u32 s79, s79, 0x100
	s_addc_u32 s80, s80, 0
	s_cmp_gt_u32 s81, 15
	s_mov_b64 s[26:27], s[28:29]
	s_cbranch_scc0 .LBB0_841
	s_and_b64 vcc, exec, s[20:21]
	s_cbranch_vccz .LBB0_844
	s_barrier

.LBB0_921:
	s_add_u32 s24, s22, 0xfff00080
	s_addc_u32 s25, s23, -1
	s_add_i32 s38, 0, 0x10000
	s_cmp_eq_u32 s79, 60
	s_cselect_b32 s27, s19, s25
	s_cselect_b32 s26, s18, s24
	s_cselect_b32 s25, s21, s78
	s_cselect_b32 s24, s20, s55
	s_add_i32 s39, 0, 0x14000
	v_add_u32_e32 v140, s38, v160
	v_add_u32_e32 v158, s39, v160
	ds_read_b128 v[120:123], v140
	ds_read_b128 v[132:135], v140 offset:1024
	ds_read_b128 v[136:139], v140 offset:2048
	ds_read_b128 v[140:143], v140 offset:3072
	ds_read_b128 v[154:157], v158
	ds_read_b128 v[162:165], v158 offset:1024
	ds_read_b128 v[166:169], v158 offset:2048
	ds_read_b128 v[170:173], v158 offset:3072
	s_add_i32 m0, s34, 0xc000
	ds_read_b128 v[178:181], v161
	ds_read_b128 v[182:185], v161 offset:1024
	ds_read_b128 v[188:191], v161 offset:2048
	ds_read_b128 v[192:195], v161 offset:3072
	ds_read_b128 v[196:199], v161 offset:4096
	ds_read_b128 v[200:203], v161 offset:5120
	ds_read_b128 v[204:207], v161 offset:6144
	ds_read_b128 v[208:211], v161 offset:7168
	global_load_lds_dwordx4 v150, s[22:23]
	s_add_i32 m0, s34, 0xe000
	s_nop 0
	global_load_lds_dwordx4 v152, s[22:23]
	s_waitcnt vmcnt(8)
	s_waitcnt lgkmcnt(0)
	s_barrier
	s_setprio 1
	s_waitcnt lgkmcnt(0)
	v_mfma_f32_16x16x32_bf16 v[128:131], v[120:123], v[178:181], v[128:131]
	v_mfma_f32_16x16x32_bf16 v[124:127], v[136:139], v[178:181], v[124:127]
	v_mfma_f32_16x16x32_bf16 v[108:111], v[120:123], v[188:191], v[108:111]
	v_mfma_f32_16x16x32_bf16 v[104:107], v[136:139], v[188:191], v[104:107]
	v_mfma_f32_16x16x32_bf16 v[92:95], v[120:123], v[196:199], v[92:95]
	v_mfma_f32_16x16x32_bf16 v[88:91], v[136:139], v[196:199], v[88:91]
	v_mfma_f32_16x16x32_bf16 v[76:79], v[120:123], v[204:207], v[76:79]
	v_mfma_f32_16x16x32_bf16 v[72:75], v[136:139], v[204:207], v[72:75]
	v_mfma_f32_16x16x32_bf16 v[128:131], v[132:135], v[182:185], v[128:131]
	v_mfma_f32_16x16x32_bf16 v[124:127], v[140:143], v[182:185], v[124:127]
	v_mfma_f32_16x16x32_bf16 v[108:111], v[132:135], v[192:195], v[108:111]
	v_mfma_f32_16x16x32_bf16 v[104:107], v[140:143], v[192:195], v[104:107]
	v_mfma_f32_16x16x32_bf16 v[92:95], v[132:135], v[200:203], v[92:95]
	v_mfma_f32_16x16x32_bf16 v[88:91], v[140:143], v[200:203], v[88:91]
	v_mfma_f32_16x16x32_bf16 v[76:79], v[132:135], v[208:211], v[76:79]
	v_mfma_f32_16x16x32_bf16 v[72:75], v[140:143], v[208:211], v[72:75]
	s_setprio 0
	s_setprio 1
	v_mfma_f32_16x16x32_bf16 v[116:119], v[154:157], v[178:181], v[116:119]
	v_mfma_f32_16x16x32_bf16 v[112:115], v[166:169], v[178:181], v[112:115]
	v_mfma_f32_16x16x32_bf16 v[100:103], v[154:157], v[188:191], v[100:103]
	v_mfma_f32_16x16x32_bf16 v[96:99], v[166:169], v[188:191], v[96:99]
	v_mfma_f32_16x16x32_bf16 v[84:87], v[154:157], v[196:199], v[84:87]
	v_mfma_f32_16x16x32_bf16 v[80:83], v[166:169], v[196:199], v[80:83]
	v_mfma_f32_16x16x32_bf16 v[68:71], v[154:157], v[204:207], v[68:71]
	v_mfma_f32_16x16x32_bf16 v[64:67], v[166:169], v[204:207], v[64:67]
	v_mfma_f32_16x16x32_bf16 v[116:119], v[162:165], v[182:185], v[116:119]
	v_mfma_f32_16x16x32_bf16 v[112:115], v[170:173], v[182:185], v[112:115]
	v_mfma_f32_16x16x32_bf16 v[100:103], v[162:165], v[192:195], v[100:103]
	v_mfma_f32_16x16x32_bf16 v[96:99], v[170:173], v[192:195], v[96:99]
	v_mfma_f32_16x16x32_bf16 v[84:87], v[162:165], v[200:203], v[84:87]
	v_mfma_f32_16x16x32_bf16 v[80:83], v[170:173], v[200:203], v[80:83]
	v_mfma_f32_16x16x32_bf16 v[68:71], v[162:165], v[208:211], v[68:71]
	v_mfma_f32_16x16x32_bf16 v[64:67], v[170:173], v[208:211], v[64:67]
	s_setprio 0
	s_barrier
	s_add_i32 s38, s38, s31
	s_add_u32 s90, s24, 0x80
	s_addc_u32 s91, s25, 0
	s_mov_b32 m0, s38
	ds_read_b128 v[178:181], v161 offset:16384
	ds_read_b128 v[182:185], v161 offset:17408
	ds_read_b128 v[188:191], v161 offset:18432
	ds_read_b128 v[192:195], v161 offset:19456
	ds_read_b128 v[196:199], v161 offset:20480
	ds_read_b128 v[200:203], v161 offset:21504
	ds_read_b128 v[204:207], v161 offset:22528
	ds_read_b128 v[208:211], v161 offset:23552
	global_load_lds_dwordx4 v176, s[24:25]
	s_add_i32 m0, s38, 0x2000
	s_add_u32 s80, s24, 0x100000
	s_addc_u32 s81, s25, 0
	s_add_i32 s38, s39, s31
	global_load_lds_dwordx4 v148, s[24:25]
	s_mov_b32 m0, s38
	s_nop 0
	global_load_lds_dwordx4 v176, s[80:81]
	s_add_i32 m0, s38, 0x2000
	s_nop 0
	global_load_lds_dwordx4 v148, s[80:81]
	s_add_u32 s96, s26, 0x80
	s_addc_u32 s97, s27, 0
	s_mov_b32 m0, s34
	s_nop 0
	global_load_lds_dwordx4 v144, s[26:27]
	s_mov_b32 m0, s35
	s_nop 0
	global_load_lds_dwordx4 v146, s[26:27]
	s_waitcnt vmcnt(8)
	s_waitcnt lgkmcnt(0)
	s_barrier
	s_setprio 1
	s_waitcnt lgkmcnt(0)
	v_mfma_f32_16x16x32_bf16 v[60:63], v[120:123], v[178:181], v[60:63]
	v_mfma_f32_16x16x32_bf16 v[56:59], v[136:139], v[178:181], v[56:59]
	v_mfma_f32_16x16x32_bf16 v[48:51], v[120:123], v[188:191], v[48:51]
	v_mfma_f32_16x16x32_bf16 v[40:43], v[136:139], v[188:191], v[40:43]
	v_mfma_f32_16x16x32_bf16 v[32:35], v[120:123], v[196:199], v[32:35]
	v_mfma_f32_16x16x32_bf16 v[24:27], v[136:139], v[196:199], v[24:27]
	v_mfma_f32_16x16x32_bf16 v[16:19], v[120:123], v[204:207], v[16:19]
	v_mfma_f32_16x16x32_bf16 v[8:11], v[136:139], v[204:207], v[8:11]
	v_mfma_f32_16x16x32_bf16 v[60:63], v[132:135], v[182:185], v[60:63]
	v_mfma_f32_16x16x32_bf16 v[56:59], v[140:143], v[182:185], v[56:59]
	v_mfma_f32_16x16x32_bf16 v[48:51], v[132:135], v[192:195], v[48:51]
	v_mfma_f32_16x16x32_bf16 v[40:43], v[140:143], v[192:195], v[40:43]
	v_mfma_f32_16x16x32_bf16 v[32:35], v[132:135], v[200:203], v[32:35]
	v_mfma_f32_16x16x32_bf16 v[24:27], v[140:143], v[200:203], v[24:27]
	v_mfma_f32_16x16x32_bf16 v[16:19], v[132:135], v[208:211], v[16:19]
	v_mfma_f32_16x16x32_bf16 v[8:11], v[140:143], v[208:211], v[8:11]
	s_setprio 0
	s_setprio 1
	v_mfma_f32_16x16x32_bf16 v[52:55], v[154:157], v[178:181], v[52:55]
	v_mfma_f32_16x16x32_bf16 v[44:47], v[166:169], v[178:181], v[44:47]
	v_mfma_f32_16x16x32_bf16 v[36:39], v[154:157], v[188:191], v[36:39]
	v_mfma_f32_16x16x32_bf16 v[28:31], v[166:169], v[188:191], v[28:31]
	v_mfma_f32_16x16x32_bf16 v[20:23], v[154:157], v[196:199], v[20:23]
	v_mfma_f32_16x16x32_bf16 v[12:15], v[166:169], v[196:199], v[12:15]
	v_mfma_f32_16x16x32_bf16 v[4:7], v[154:157], v[204:207], v[4:7]
	v_mfma_f32_16x16x32_bf16 v[0:3], v[166:169], v[204:207], v[0:3]
	v_mfma_f32_16x16x32_bf16 v[52:55], v[162:165], v[182:185], v[52:55]
	v_mfma_f32_16x16x32_bf16 v[44:47], v[170:173], v[182:185], v[44:47]
	v_mfma_f32_16x16x32_bf16 v[36:39], v[162:165], v[192:195], v[36:39]
	v_mfma_f32_16x16x32_bf16 v[28:31], v[170:173], v[192:195], v[28:31]
	v_mfma_f32_16x16x32_bf16 v[20:23], v[162:165], v[200:203], v[20:23]
	v_mfma_f32_16x16x32_bf16 v[12:15], v[170:173], v[200:203], v[12:15]
	v_mfma_f32_16x16x32_bf16 v[4:7], v[162:165], v[208:211], v[4:7]
	v_mfma_f32_16x16x32_bf16 v[0:3], v[170:173], v[208:211], v[0:3]
	s_setprio 0
	s_barrier
	s_add_i32 s38, 0, 0x18000
	s_add_i32 s39, 0, 0x1c000
	v_add_u32_e32 v140, s38, v160
	v_add_u32_e32 v170, s39, v160
	ds_read_b128 v[120:123], v140
	ds_read_b128 v[132:135], v140 offset:1024
	ds_read_b128 v[136:139], v140 offset:2048
	ds_read_b128 v[140:143], v140 offset:3072
	ds_read_b128 v[154:157], v170
	ds_read_b128 v[162:165], v170 offset:1024
	ds_read_b128 v[166:169], v170 offset:2048
	ds_read_b128 v[170:173], v170 offset:3072
	s_add_u32 s26, s26, 0x100000
	s_addc_u32 s27, s27, 0
	s_mov_b32 m0, s36
	ds_read_b128 v[178:181], v161 offset:32768
	ds_read_b128 v[182:185], v161 offset:33792
	ds_read_b128 v[188:191], v161 offset:34816
	ds_read_b128 v[192:195], v161 offset:35840
	ds_read_b128 v[196:199], v161 offset:36864
	ds_read_b128 v[200:203], v161 offset:37888
	ds_read_b128 v[204:207], v161 offset:38912
	ds_read_b128 v[208:211], v161 offset:39936
	global_load_lds_dwordx4 v144, s[26:27]
	s_mov_b32 m0, s43
	s_nop 0
	global_load_lds_dwordx4 v146, s[26:27]
	s_waitcnt vmcnt(8)
	s_waitcnt lgkmcnt(0)
	s_barrier
	s_setprio 1
	s_waitcnt lgkmcnt(0)
	v_mfma_f32_16x16x32_bf16 v[128:131], v[120:123], v[178:181], v[128:131]
	v_mfma_f32_16x16x32_bf16 v[124:127], v[136:139], v[178:181], v[124:127]
	v_mfma_f32_16x16x32_bf16 v[108:111], v[120:123], v[188:191], v[108:111]
	v_mfma_f32_16x16x32_bf16 v[104:107], v[136:139], v[188:191], v[104:107]
	v_mfma_f32_16x16x32_bf16 v[92:95], v[120:123], v[196:199], v[92:95]
	v_mfma_f32_16x16x32_bf16 v[88:91], v[136:139], v[196:199], v[88:91]
	v_mfma_f32_16x16x32_bf16 v[76:79], v[120:123], v[204:207], v[76:79]
	v_mfma_f32_16x16x32_bf16 v[72:75], v[136:139], v[204:207], v[72:75]
	v_mfma_f32_16x16x32_bf16 v[128:131], v[132:135], v[182:185], v[128:131]
	v_mfma_f32_16x16x32_bf16 v[124:127], v[140:143], v[182:185], v[124:127]
	v_mfma_f32_16x16x32_bf16 v[108:111], v[132:135], v[192:195], v[108:111]
	v_mfma_f32_16x16x32_bf16 v[104:107], v[140:143], v[192:195], v[104:107]
	v_mfma_f32_16x16x32_bf16 v[92:95], v[132:135], v[200:203], v[92:95]
	v_mfma_f32_16x16x32_bf16 v[88:91], v[140:143], v[200:203], v[88:91]
	v_mfma_f32_16x16x32_bf16 v[76:79], v[132:135], v[208:211], v[76:79]
	v_mfma_f32_16x16x32_bf16 v[72:75], v[140:143], v[208:211], v[72:75]
	s_setprio 0
	s_setprio 1
	v_mfma_f32_16x16x32_bf16 v[116:119], v[154:157], v[178:181], v[116:119]
	v_mfma_f32_16x16x32_bf16 v[112:115], v[166:169], v[178:181], v[112:115]
	v_mfma_f32_16x16x32_bf16 v[100:103], v[154:157], v[188:191], v[100:103]
	v_mfma_f32_16x16x32_bf16 v[96:99], v[166:169], v[188:191], v[96:99]
	v_mfma_f32_16x16x32_bf16 v[84:87], v[154:157], v[196:199], v[84:87]
	v_mfma_f32_16x16x32_bf16 v[80:83], v[166:169], v[196:199], v[80:83]
	v_mfma_f32_16x16x32_bf16 v[68:71], v[154:157], v[204:207], v[68:71]
	v_mfma_f32_16x16x32_bf16 v[64:67], v[166:169], v[204:207], v[64:67]
	v_mfma_f32_16x16x32_bf16 v[116:119], v[162:165], v[182:185], v[116:119]
	v_mfma_f32_16x16x32_bf16 v[112:115], v[170:173], v[182:185], v[112:115]
	v_mfma_f32_16x16x32_bf16 v[100:103], v[162:165], v[192:195], v[100:103]
	v_mfma_f32_16x16x32_bf16 v[96:99], v[170:173], v[192:195], v[96:99]
	v_mfma_f32_16x16x32_bf16 v[84:87], v[162:165], v[200:203], v[84:87]
	v_mfma_f32_16x16x32_bf16 v[80:83], v[170:173], v[200:203], v[80:83]
	v_mfma_f32_16x16x32_bf16 v[68:71], v[162:165], v[208:211], v[68:71]
	v_mfma_f32_16x16x32_bf16 v[64:67], v[170:173], v[208:211], v[64:67]
	s_setprio 0
	s_barrier
	s_add_i32 s26, s38, s31
	s_mov_b32 m0, s26
	ds_read_b128 v[178:181], v161 offset:49152
	ds_read_b128 v[182:185], v161 offset:50176
	ds_read_b128 v[188:191], v161 offset:51200
	ds_read_b128 v[192:195], v161 offset:52224
	ds_read_b128 v[196:199], v161 offset:53248
	ds_read_b128 v[200:203], v161 offset:54272
	ds_read_b128 v[204:207], v161 offset:55296
	ds_read_b128 v[208:211], v161 offset:56320
	global_load_lds_dwordx4 v176, s[90:91]
	s_add_i32 m0, s26, 0x2000
	s_add_u32 s24, s24, 0x100080
	s_addc_u32 s25, s25, 0
	s_add_i32 s26, s39, s31
	global_load_lds_dwordx4 v148, s[90:91]
	s_mov_b32 m0, s26
	s_nop 0
	global_load_lds_dwordx4 v176, s[24:25]
	s_add_i32 m0, s26, 0x2000
	s_nop 0
	global_load_lds_dwordx4 v148, s[24:25]
	s_mov_b32 m0, s49
	s_nop 0
	global_load_lds_dwordx4 v144, s[96:97]
	s_mov_b32 m0, s50
	s_nop 0
	global_load_lds_dwordx4 v146, s[96:97]
	s_waitcnt vmcnt(8)
	s_waitcnt lgkmcnt(0)
	s_barrier
	s_setprio 1
	s_waitcnt lgkmcnt(0)
	v_mfma_f32_16x16x32_bf16 v[60:63], v[120:123], v[178:181], v[60:63]
	v_mfma_f32_16x16x32_bf16 v[56:59], v[136:139], v[178:181], v[56:59]
	v_mfma_f32_16x16x32_bf16 v[48:51], v[120:123], v[188:191], v[48:51]
	v_mfma_f32_16x16x32_bf16 v[40:43], v[136:139], v[188:191], v[40:43]
	v_mfma_f32_16x16x32_bf16 v[32:35], v[120:123], v[196:199], v[32:35]
	v_mfma_f32_16x16x32_bf16 v[24:27], v[136:139], v[196:199], v[24:27]
	v_mfma_f32_16x16x32_bf16 v[16:19], v[120:123], v[204:207], v[16:19]
	v_mfma_f32_16x16x32_bf16 v[8:11], v[136:139], v[204:207], v[8:11]
	v_mfma_f32_16x16x32_bf16 v[60:63], v[132:135], v[182:185], v[60:63]
	v_mfma_f32_16x16x32_bf16 v[56:59], v[140:143], v[182:185], v[56:59]
	v_mfma_f32_16x16x32_bf16 v[48:51], v[132:135], v[192:195], v[48:51]
	v_mfma_f32_16x16x32_bf16 v[40:43], v[140:143], v[192:195], v[40:43]
	v_mfma_f32_16x16x32_bf16 v[32:35], v[132:135], v[200:203], v[32:35]
	v_mfma_f32_16x16x32_bf16 v[24:27], v[140:143], v[200:203], v[24:27]
	v_mfma_f32_16x16x32_bf16 v[16:19], v[132:135], v[208:211], v[16:19]
	v_mfma_f32_16x16x32_bf16 v[8:11], v[140:143], v[208:211], v[8:11]
	s_setprio 0
	s_setprio 1
	v_mfma_f32_16x16x32_bf16 v[52:55], v[154:157], v[178:181], v[52:55]
	v_mfma_f32_16x16x32_bf16 v[44:47], v[166:169], v[178:181], v[44:47]
	v_mfma_f32_16x16x32_bf16 v[36:39], v[154:157], v[188:191], v[36:39]
	v_mfma_f32_16x16x32_bf16 v[28:31], v[166:169], v[188:191], v[28:31]
	v_mfma_f32_16x16x32_bf16 v[20:23], v[154:157], v[196:199], v[20:23]
	v_mfma_f32_16x16x32_bf16 v[12:15], v[166:169], v[196:199], v[12:15]
	v_mfma_f32_16x16x32_bf16 v[4:7], v[154:157], v[204:207], v[4:7]
	v_mfma_f32_16x16x32_bf16 v[0:3], v[166:169], v[204:207], v[0:3]
	v_mfma_f32_16x16x32_bf16 v[52:55], v[162:165], v[182:185], v[52:55]
	v_mfma_f32_16x16x32_bf16 v[44:47], v[170:173], v[182:185], v[44:47]
	v_mfma_f32_16x16x32_bf16 v[36:39], v[162:165], v[192:195], v[36:39]
	v_mfma_f32_16x16x32_bf16 v[28:31], v[170:173], v[192:195], v[28:31]
	v_mfma_f32_16x16x32_bf16 v[20:23], v[162:165], v[200:203], v[20:23]
	v_mfma_f32_16x16x32_bf16 v[12:15], v[170:173], v[200:203], v[12:15]
	v_mfma_f32_16x16x32_bf16 v[4:7], v[162:165], v[208:211], v[4:7]
	v_mfma_f32_16x16x32_bf16 v[0:3], v[170:173], v[208:211], v[0:3]
	s_setprio 0
	s_barrier
	s_add_i32 s79, s79, 2
	s_add_u32 s22, s22, 0x100
	s_addc_u32 s23, s23, 0
	s_add_u32 s55, s55, 0x100
	s_addc_u32 s78, s78, 0
	s_cmp_gt_u32 s79, 61
	s_cbranch_scc0 .LBB0_921
	s_and_b64 vcc, exec, s[8:9]
	s_cbranch_vccz .LBB0_924
	s_barrier
